# P3 chain: scan preamble runs under its 66 loads; ctx chunk sums issue all 48 fragment loads up front
# speedup vs baseline: 1.0044x; 1.0001x over previous
; #define LAS __attribute__((address_space(3)))
; __device__ __forceinline__ void ssm_scan(LAS float* L, int item, const float* lam_re, const float* lam_im, const float* log_dt, const float* S, f16* X) {
;     const int b = item >> 7, dir = (item >> 6) & 1, g = item & 63;
;     int tid = threadIdx.x; asm volatile("" : "+v"(tid));
;     const int seg = tid >> 6, n = tid & 63, pg = dir * NG + g;
;     const float dt = expf(log_dt[pg]), lr = lam_re[pg * NS + n], li = lam_im[pg * NS + n];
;     float tr, ti, sr, si;
;     { const float er = expf((float)TC * lr * dt); float sn, cs; sincosf((float)TC * (li * dt), &sn, &cs); tr = er * cs; ti = er * sn; }
;     { const float er = expf((float)(33 * TC) * lr * dt); float sn, cs; sincosf((float)(33 * TC) * (li * dt), &sn, &cs); sr = er * cs; si = er * sn; }
;     const float* Sg = S + (size_t)g * NCH * 256 + dir * 128 + n;
;     f16* Xg = X + (size_t)g * XGS + dir * 128 + n;
;     float vr[33], vi[33];
; #pragma unroll
;     for (int i = 0; i < 33; ++i) { const int p = seg * 33 + i;
;         const int row = p < 8 ? NLC + b * 8 + (dir == 0 ? p : 7 - p) : b * 256 + (dir == 0 ? p - 8 : 255 - (p - 8));
;         vr[i] = Sg[(size_t)row * 256]; vi[i] = Sg[(size_t)row * 256 + 64]; }
.LBB0_758:
	s_or_b64 exec, exec, s[2:3]
	s_bfe_u32 s31, s81, 0x60002
	s_lshl_b32 s0, s31, 2
	v_mov_b32_e32 v2, s0
	v_readlane_b32 s0, v254, 18
	v_mov_b32_e32 v37, v0
	v_readlane_b32 s8, v254, 26
	v_readlane_b32 s9, v254, 27
	s_barrier
	s_lshl_b32 s0, s31, 8
	s_nop 2
	global_load_dword v150, v2, s[8:9] offset:256
	v_and_b32_e32 v33, 63, v37
	v_lshl_or_b32 v3, v33, 2, s0
	v_readlane_b32 s6, v254, 24
	v_readlane_b32 s7, v254, 25
	v_or_b32_e32 v3, 0x4000, v3
	v_readlane_b32 s4, v254, 22
	v_readlane_b32 s5, v254, 23
	s_nop 1
	global_load_dword v152, v3, s[6:7]
	s_nop 1
	global_load_dword v30, v3, s[4:5]
	s_lshl_b32 s0, s84, 7
	s_or_b32 s0, s0, s24
	s_ashr_i32 s2, s0, 7
	s_mul_i32 s0, s31, 0x84000
	s_add_u32 s0, s50, s0
	v_mov_b32_e32 v3, 0
	s_addc_u32 s1, s51, 0
	v_lshlrev_b32_e32 v2, 2, v33
	v_lshl_add_u64 v[4:5], s[0:1], 0, v[2:3]
	s_mov_b64 s[0:1], 0x15600200
	v_lshl_add_u64 v[4:5], v[4:5], 0, s[0:1]
	s_lshl_b32 s0, s2, 8
	s_lshl_b32 s2, s2, 3
	v_ashrrev_i32_e32 v39, 6, v37
	s_add_i32 s3, s2, 0x207
	s_add_i32 s66, s0, 0x107
	v_mov_b32_e32 v2, s66
	v_mov_b32_e32 v6, s3
	v_cmp_gt_i32_e32 vcc, 1, v39
	v_lshl_add_u32 v31, v39, 5, v39
	s_add_i32 s3, s2, 0x206
	v_cndmask_b32_e32 v2, v2, v6, vcc
	s_add_i32 s65, s0, 0x106
	v_sub_u32_e32 v6, v2, v31
	v_mov_b32_e32 v2, s65
	v_mov_b32_e32 v8, s3
	v_cndmask_b32_e32 v2, v2, v8, vcc
	v_sub_u32_e32 v8, v2, v31
	v_ashrrev_i32_e32 v9, 31, v8
	v_lshlrev_b64 v[8:9], 10, v[8:9]
	s_add_i32 s3, s2, 0x205
	s_add_i32 s64, s0, 0x105
	v_lshl_add_u64 v[10:11], v[4:5], 0, v[8:9]
	v_mov_b32_e32 v2, s64
	v_mov_b32_e32 v8, s3
	v_cndmask_b32_e32 v2, v2, v8, vcc
	v_sub_u32_e32 v8, v2, v31
	v_ashrrev_i32_e32 v9, 31, v8
	v_lshlrev_b64 v[8:9], 10, v[8:9]
	s_add_i32 s3, s2, 0x204
	s_add_i32 s63, s0, 0x104
	v_lshl_add_u64 v[12:13], v[4:5], 0, v[8:9]
	v_mov_b32_e32 v2, s63
	v_mov_b32_e32 v8, s3
	v_cndmask_b32_e32 v2, v2, v8, vcc
	v_ashrrev_i32_e32 v7, 31, v6
	v_sub_u32_e32 v8, v2, v31
	v_lshlrev_b64 v[6:7], 10, v[6:7]
	v_ashrrev_i32_e32 v9, 31, v8
	v_lshl_add_u64 v[6:7], v[4:5], 0, v[6:7]
	v_lshlrev_b64 v[8:9], 10, v[8:9]
	s_add_i32 s3, s2, 0x203
	s_add_i32 s62, s0, 0x103
	v_lshl_add_u64 v[14:15], v[4:5], 0, v[8:9]
	global_load_dword v8, v[6:7], off
	global_load_dword v9, v[6:7], off offset:256
	global_load_dword v42, v[10:11], off
	global_load_dword v44, v[10:11], off offset:256
	s_nop 0
	global_load_dword v6, v[12:13], off
	global_load_dword v7, v[12:13], off offset:256
	global_load_dword v50, v[14:15], off
	global_load_dword v52, v[14:15], off offset:256
	v_mov_b32_e32 v2, s62
	v_mov_b32_e32 v10, s3
	v_cndmask_b32_e32 v2, v2, v10, vcc
	s_add_i32 s3, s2, 0x202
	s_add_i32 s61, s0, 0x102
	v_sub_u32_e32 v10, v2, v31
	v_mov_b32_e32 v2, s61
	v_mov_b32_e32 v12, s3
	v_cndmask_b32_e32 v2, v2, v12, vcc
	v_sub_u32_e32 v12, v2, v31
	v_ashrrev_i32_e32 v13, 31, v12
	v_lshlrev_b64 v[12:13], 10, v[12:13]
	s_add_i32 s3, s2, 0x201
	s_add_i32 s60, s0, 0x101
	v_lshl_add_u64 v[14:15], v[4:5], 0, v[12:13]
	v_mov_b32_e32 v2, s60
	v_mov_b32_e32 v12, s3
	v_cndmask_b32_e32 v2, v2, v12, vcc
	v_sub_u32_e32 v12, v2, v31
	v_ashrrev_i32_e32 v13, 31, v12
	s_add_i32 s1, s2, 0x200
	v_lshlrev_b64 v[12:13], 10, v[12:13]
	s_add_i32 s59, s0, 0x100
	v_lshl_add_u64 v[16:17], v[4:5], 0, v[12:13]
	v_mov_b32_e32 v2, s59
	v_mov_b32_e32 v12, s1
	v_cndmask_b32_e32 v2, v2, v12, vcc
	v_ashrrev_i32_e32 v11, 31, v10
	v_sub_u32_e32 v12, v2, v31
	v_lshlrev_b64 v[10:11], 10, v[10:11]
	v_ashrrev_i32_e32 v13, 31, v12
	v_xad_u32 v2, v31, -1, s1
	s_or_b32 s1, s0, 0xff
	v_lshl_add_u64 v[10:11], v[4:5], 0, v[10:11]
	v_lshlrev_b64 v[12:13], 10, v[12:13]
	v_sub_u32_e32 v43, s1, v31
	v_cmp_gt_i32_e32 vcc, 0, v39
	s_add_i32 s1, s2, 0x1fe
	s_or_b32 s58, s0, 0xfe
	v_lshl_add_u64 v[18:19], v[4:5], 0, v[12:13]
	global_load_dword v12, v[10:11], off
	global_load_dword v13, v[10:11], off offset:256
	global_load_dword v58, v[14:15], off
	global_load_dword v62, v[14:15], off offset:256
	s_nop 0
	global_load_dword v10, v[16:17], off
	global_load_dword v11, v[16:17], off offset:256
	global_load_dword v63, v[18:19], off
	global_load_dword v64, v[18:19], off offset:256
	v_cndmask_b32_e32 v14, v43, v2, vcc
	v_mov_b32_e32 v2, s58
	v_mov_b32_e32 v16, s1
	v_cndmask_b32_e32 v2, v2, v16, vcc
	v_sub_u32_e32 v16, v2, v31
	v_ashrrev_i32_e32 v17, 31, v16
	v_lshlrev_b64 v[16:17], 10, v[16:17]
	s_add_i32 s1, s2, 0x1fd
	s_or_b32 s57, s0, 0xfd
	v_lshl_add_u64 v[18:19], v[4:5], 0, v[16:17]
	v_mov_b32_e32 v2, s57
	v_mov_b32_e32 v16, s1
	v_cndmask_b32_e32 v2, v2, v16, vcc
	v_sub_u32_e32 v16, v2, v31
	v_ashrrev_i32_e32 v17, 31, v16
	v_lshlrev_b64 v[16:17], 10, v[16:17]
	s_add_i32 s1, s2, 0x1fc
	s_or_b32 s56, s0, 0xfc
	v_lshl_add_u64 v[20:21], v[4:5], 0, v[16:17]
	v_mov_b32_e32 v2, s56
	v_mov_b32_e32 v16, s1
	v_cndmask_b32_e32 v2, v2, v16, vcc
	v_ashrrev_i32_e32 v15, 31, v14
	v_sub_u32_e32 v16, v2, v31
	v_lshlrev_b64 v[14:15], 10, v[14:15]
	v_ashrrev_i32_e32 v17, 31, v16
	v_lshl_add_u64 v[14:15], v[4:5], 0, v[14:15]
	v_lshlrev_b64 v[16:17], 10, v[16:17]
	s_add_i32 s1, s2, 0x1fb
	s_or_b32 s55, s0, 0xfb
	v_lshl_add_u64 v[22:23], v[4:5], 0, v[16:17]
	global_load_dword v16, v[14:15], off
	global_load_dword v17, v[14:15], off offset:256
	global_load_dword v66, v[18:19], off
	global_load_dword v68, v[18:19], off offset:256
	s_nop 0
	global_load_dword v14, v[20:21], off
	global_load_dword v15, v[20:21], off offset:256
	global_load_dword v69, v[22:23], off
	global_load_dword v72, v[22:23], off offset:256
	v_mov_b32_e32 v2, s55
	v_mov_b32_e32 v18, s1
	v_cndmask_b32_e32 v2, v2, v18, vcc
	s_add_i32 s1, s2, 0x1fa
	s_or_b32 s54, s0, 0xfa
	v_sub_u32_e32 v18, v2, v31
	v_mov_b32_e32 v2, s54
	v_mov_b32_e32 v20, s1
; __device__ __forceinline__ void ssm_scan(LAS float* L, int item, const float* lam_re, const float* lam_im, const float* log_dt, const float* S, f16* X) {
;     ...
;     for (int i = 0; i < 33; ++i) { const int p = seg * 33 + i;
;         const int row = p < 8 ? NLC + b * 8 + (dir == 0 ? p : 7 - p) : b * 256 + (dir == 0 ? p - 8 : 255 - (p - 8));
;         vr[i] = Sg[(size_t)row * 256]; vi[i] = Sg[(size_t)row * 256 + 64]; }
	v_cndmask_b32_e32 v2, v2, v20, vcc
	v_sub_u32_e32 v20, v2, v31
	v_ashrrev_i32_e32 v21, 31, v20
	v_lshlrev_b64 v[20:21], 10, v[20:21]
	s_add_i32 s1, s2, 0x1f9
	s_or_b32 s45, s0, 0xf9
	v_lshl_add_u64 v[22:23], v[4:5], 0, v[20:21]
	v_mov_b32_e32 v2, s45
	v_mov_b32_e32 v20, s1
	v_cndmask_b32_e32 v2, v2, v20, vcc
	v_sub_u32_e32 v20, v2, v31
	v_ashrrev_i32_e32 v21, 31, v20
	v_lshlrev_b64 v[20:21], 10, v[20:21]
	s_add_i32 s1, s2, 0x1f8
	s_or_b32 s44, s0, 0xf8
	v_lshl_add_u64 v[24:25], v[4:5], 0, v[20:21]
	v_mov_b32_e32 v2, s44
	v_mov_b32_e32 v20, s1
	v_cndmask_b32_e32 v2, v2, v20, vcc
	v_ashrrev_i32_e32 v19, 31, v18
	v_sub_u32_e32 v20, v2, v31
	v_lshlrev_b64 v[18:19], 10, v[18:19]
	v_ashrrev_i32_e32 v21, 31, v20
	v_lshl_add_u64 v[18:19], v[4:5], 0, v[18:19]
	v_lshlrev_b64 v[20:21], 10, v[20:21]
	s_add_i32 s1, s2, 0x1f7
	s_or_b32 s41, s0, 0xf7
	v_lshl_add_u64 v[26:27], v[4:5], 0, v[20:21]
	global_load_dword v20, v[18:19], off
	global_load_dword v21, v[18:19], off offset:256
	global_load_dword v85, v[22:23], off
	global_load_dword v89, v[22:23], off offset:256
	s_nop 0
	global_load_dword v18, v[24:25], off
	global_load_dword v19, v[24:25], off offset:256
	global_load_dword v91, v[26:27], off
	global_load_dword v95, v[26:27], off offset:256
	v_mov_b32_e32 v2, s41
	v_mov_b32_e32 v22, s1
	v_cndmask_b32_e32 v2, v2, v22, vcc
	s_add_i32 s1, s2, 0x1f6
	s_or_b32 s40, s0, 0xf6
	v_sub_u32_e32 v22, v2, v31
	v_mov_b32_e32 v2, s40
	v_mov_b32_e32 v24, s1
	v_cndmask_b32_e32 v2, v2, v24, vcc
	v_sub_u32_e32 v24, v2, v31
	v_ashrrev_i32_e32 v25, 31, v24
	v_lshlrev_b64 v[24:25], 10, v[24:25]
	s_add_i32 s1, s2, 0x1f5
	s_or_b32 s37, s0, 0xf5
	v_lshl_add_u64 v[26:27], v[4:5], 0, v[24:25]
	v_mov_b32_e32 v2, s37
	v_mov_b32_e32 v24, s1
	v_cndmask_b32_e32 v2, v2, v24, vcc
	v_sub_u32_e32 v24, v2, v31
	v_ashrrev_i32_e32 v25, 31, v24
	v_lshlrev_b64 v[24:25], 10, v[24:25]
	s_add_i32 s1, s2, 0x1f4
	s_or_b32 s36, s0, 0xf4
	v_lshl_add_u64 v[28:29], v[4:5], 0, v[24:25]
	v_mov_b32_e32 v2, s36
	v_mov_b32_e32 v24, s1
	v_cndmask_b32_e32 v2, v2, v24, vcc
	v_ashrrev_i32_e32 v23, 31, v22
	v_sub_u32_e32 v24, v2, v31
	v_lshlrev_b64 v[22:23], 10, v[22:23]
	v_ashrrev_i32_e32 v25, 31, v24
	v_lshl_add_u64 v[22:23], v[4:5], 0, v[22:23]
	v_lshlrev_b64 v[24:25], 10, v[24:25]
	s_add_i32 s1, s2, 0x1f3
	s_or_b32 s35, s0, 0xf3
	v_lshl_add_u64 v[40:41], v[4:5], 0, v[24:25]
	global_load_dword v24, v[22:23], off
	global_load_dword v25, v[22:23], off offset:256
	global_load_dword v97, v[26:27], off
	global_load_dword v101, v[26:27], off offset:256
	s_nop 0
	global_load_dword v22, v[28:29], off
	global_load_dword v23, v[28:29], off offset:256
	global_load_dword v103, v[40:41], off
	global_load_dword v114, v[40:41], off offset:256
	v_mov_b32_e32 v2, s35
	v_mov_b32_e32 v26, s1
	v_cndmask_b32_e32 v2, v2, v26, vcc
	s_add_i32 s1, s2, 0x1f2
	s_or_b32 s33, s0, 0xf2
	v_sub_u32_e32 v26, v2, v31
	v_mov_b32_e32 v2, s33
	v_mov_b32_e32 v28, s1
	v_cndmask_b32_e32 v2, v2, v28, vcc
	v_sub_u32_e32 v28, v2, v31
	v_ashrrev_i32_e32 v29, 31, v28
	v_lshlrev_b64 v[28:29], 10, v[28:29]
	s_add_i32 s1, s2, 0x1f1
	s_or_b32 s25, s0, 0xf1
	v_lshl_add_u64 v[40:41], v[4:5], 0, v[28:29]
	v_mov_b32_e32 v2, s25
	v_mov_b32_e32 v28, s1
	v_cndmask_b32_e32 v2, v2, v28, vcc
	v_sub_u32_e32 v28, v2, v31
	v_ashrrev_i32_e32 v29, 31, v28
	v_lshlrev_b64 v[28:29], 10, v[28:29]
	s_add_i32 s1, s2, 0x1f0
	s_or_b32 s21, s0, 0xf0
	v_lshl_add_u64 v[46:47], v[4:5], 0, v[28:29]
	v_mov_b32_e32 v2, s21
	v_mov_b32_e32 v28, s1
	v_cndmask_b32_e32 v2, v2, v28, vcc
	v_ashrrev_i32_e32 v27, 31, v26
	v_sub_u32_e32 v28, v2, v31
	v_lshlrev_b64 v[26:27], 10, v[26:27]
	v_ashrrev_i32_e32 v29, 31, v28
	v_lshl_add_u64 v[26:27], v[4:5], 0, v[26:27]
	v_lshlrev_b64 v[28:29], 10, v[28:29]
	s_add_i32 s1, s2, 0x1ef
	s_or_b32 s20, s0, 0xef
	v_lshl_add_u64 v[48:49], v[4:5], 0, v[28:29]
	global_load_dword v28, v[26:27], off
	global_load_dword v29, v[26:27], off offset:256
	global_load_dword v115, v[40:41], off
	global_load_dword v116, v[40:41], off offset:256
	s_nop 0
	global_load_dword v26, v[46:47], off
	global_load_dword v27, v[46:47], off offset:256
	global_load_dword v117, v[48:49], off
	global_load_dword v118, v[48:49], off offset:256
	v_mov_b32_e32 v2, s20
	v_mov_b32_e32 v40, s1
	v_cndmask_b32_e32 v2, v2, v40, vcc
	s_add_i32 s1, s2, 0x1ee
	s_or_b32 s15, s0, 0xee
	v_sub_u32_e32 v40, v2, v31
	v_mov_b32_e32 v2, s15
	v_mov_b32_e32 v46, s1
	v_cndmask_b32_e32 v2, v2, v46, vcc
	s_add_i32 s1, s2, 0x1ed
	s_or_b32 s14, s0, 0xed
	v_sub_u32_e32 v46, v2, v31
	v_mov_b32_e32 v2, s14
	v_mov_b32_e32 v48, s1
	v_cndmask_b32_e32 v2, v2, v48, vcc
	v_sub_u32_e32 v48, v2, v31
	v_ashrrev_i32_e32 v49, 31, v48
	v_lshlrev_b64 v[48:49], 10, v[48:49]
	s_add_i32 s1, s2, 0x1ec
	s_or_b32 s13, s0, 0xec
	v_lshl_add_u64 v[56:57], v[4:5], 0, v[48:49]
	v_mov_b32_e32 v2, s13
	v_mov_b32_e32 v48, s1
	v_cndmask_b32_e32 v2, v2, v48, vcc
	v_ashrrev_i32_e32 v41, 31, v40
	v_sub_u32_e32 v48, v2, v31
	v_lshlrev_b64 v[40:41], 10, v[40:41]
	v_ashrrev_i32_e32 v47, 31, v46
	v_ashrrev_i32_e32 v49, 31, v48
	v_lshl_add_u64 v[40:41], v[4:5], 0, v[40:41]
	v_lshlrev_b64 v[46:47], 10, v[46:47]
	v_lshlrev_b64 v[48:49], 10, v[48:49]
	s_add_i32 s1, s2, 0x1eb
	s_or_b32 s12, s0, 0xeb
	v_lshl_add_u64 v[46:47], v[4:5], 0, v[46:47]
	v_lshl_add_u64 v[60:61], v[4:5], 0, v[48:49]
	global_load_dword v54, v[40:41], off
	global_load_dword v55, v[40:41], off offset:256
	global_load_dword v119, v[46:47], off
	global_load_dword v120, v[46:47], off offset:256
	global_load_dword v48, v[56:57], off
	global_load_dword v49, v[56:57], off offset:256
	global_load_dword v121, v[60:61], off
	global_load_dword v122, v[60:61], off offset:256
	v_mov_b32_e32 v2, s12
; __device__ __forceinline__ void ssm_scan(LAS float* L, int item, const float* lam_re, const float* lam_im, const float* log_dt, const float* S, f16* X) {
;     ...
;     const float dt = expf(log_dt[pg]), lr = lam_re[pg * NS + n], li = lam_im[pg * NS + n];
;     float tr, ti, sr, si;
;     { const float er = expf((float)TC * lr * dt); float sn, cs; sincosf((float)TC * (li * dt), &sn, &cs); tr = er * cs; ti = er * sn; }
;     { const float er = expf((float)(33 * TC) * lr * dt); float sn, cs; sincosf((float)(33 * TC) * (li * dt), &sn, &cs); sr = er * cs; si = er * sn; }
;     ...
;     for (int i = 0; i < 33; ++i) { const int p = seg * 33 + i;
;         const int row = p < 8 ? NLC + b * 8 + (dir == 0 ? p : 7 - p) : b * 256 + (dir == 0 ? p - 8 : 255 - (p - 8));
;         vr[i] = Sg[(size_t)row * 256]; vi[i] = Sg[(size_t)row * 256 + 64]; }
	v_mov_b32_e32 v40, s1
	v_cndmask_b32_e32 v2, v2, v40, vcc
	s_add_i32 s1, s2, 0x1ea
	s_or_b32 s11, s0, 0xea
	v_sub_u32_e32 v40, v2, v31
	v_mov_b32_e32 v2, s11
	v_mov_b32_e32 v46, s1
	v_cndmask_b32_e32 v2, v2, v46, vcc
	s_add_i32 s1, s2, 0x1e9
	s_or_b32 s10, s0, 0xe9
	v_sub_u32_e32 v46, v2, v31
	v_mov_b32_e32 v2, s10
	v_mov_b32_e32 v56, s1
	v_cndmask_b32_e32 v2, v2, v56, vcc
	s_add_i32 s3, s2, 0x1e8
	s_or_b32 s1, s0, 0xe8
	v_sub_u32_e32 v56, v2, v31
	v_mov_b32_e32 v2, s1
	v_mov_b32_e32 v60, s3
	v_cndmask_b32_e32 v2, v2, v60, vcc
	v_ashrrev_i32_e32 v41, 31, v40
	v_sub_u32_e32 v60, v2, v31
	v_lshlrev_b64 v[40:41], 10, v[40:41]
	v_ashrrev_i32_e32 v47, 31, v46
	v_ashrrev_i32_e32 v57, 31, v56
	v_ashrrev_i32_e32 v61, 31, v60
	v_lshl_add_u64 v[40:41], v[4:5], 0, v[40:41]
	v_lshlrev_b64 v[46:47], 10, v[46:47]
	v_lshlrev_b64 v[56:57], 10, v[56:57]
	v_lshlrev_b64 v[60:61], 10, v[60:61]
	s_addk_i32 s2, 0x1e7
	s_or_b32 s0, s0, 0xe7
	v_lshl_add_u64 v[46:47], v[4:5], 0, v[46:47]
	v_lshl_add_u64 v[56:57], v[4:5], 0, v[56:57]
	v_lshl_add_u64 v[60:61], v[4:5], 0, v[60:61]
	global_load_dword v112, v[40:41], off
	global_load_dword v113, v[40:41], off offset:256
	global_load_dword v123, v[46:47], off
	global_load_dword v124, v[46:47], off offset:256
	global_load_dword v110, v[56:57], off
	global_load_dword v111, v[56:57], off offset:256
	global_load_dword v125, v[60:61], off
	global_load_dword v126, v[60:61], off offset:256
	v_mov_b32_e32 v2, s0
	v_mov_b32_e32 v40, s2
	v_cndmask_b32_e32 v2, v2, v40, vcc
	v_sub_u32_e32 v40, v2, v31
	v_ashrrev_i32_e32 v41, 31, v40
	v_lshlrev_b64 v[40:41], 10, v[40:41]
	v_lshl_add_u64 v[4:5], v[4:5], 0, v[40:41]
	global_load_dword v108, v[4:5], off
	global_load_dword v109, v[4:5], off offset:256
	s_mov_b64 s[96:97], vcc
	s_mov_b32 s72, 0x3fb8aa3b
	v_readlane_b32 s73, v254, 19
	s_mov_b32 s73, 0xc2ce8ed0
	v_readlane_b32 s2, v254, 20
	s_brev_b32 s2, 18
	v_readlane_b32 s3, v254, 21
	v_readlane_b32 s74, v254, 28
	v_readlane_b32 s75, v254, 29
	v_readlane_b32 s76, v254, 30
	v_readlane_b32 s77, v254, 31
	v_readlane_b32 s94, v254, 32
	v_readlane_b32 s95, v254, 33
	s_waitcnt vmcnt(63)
	v_mul_f32_e32 v151, 0x3fb8aa3b, v150
	v_fma_f32 v153, v150, s72, -v151
	v_rndne_f32_e32 v154, v151
	v_fmamk_f32 v153, v150, 0x32a5705f, v153
	v_sub_f32_e32 v151, v151, v154
	v_add_f32_e32 v151, v151, v153
	v_cvt_i32_f32_e32 v154, v154
	v_exp_f32_e32 v151, v151
	s_mov_b32 s72, 0x42b17218
	v_cmp_ngt_f32_e32 vcc, s73, v150
	v_mov_b32_e32 v153, 0x7f800000
	v_ldexp_f32 v151, v151, v154
	v_cndmask_b32_e32 v151, 0, v151, vcc
	v_cmp_nlt_f32_e32 vcc, s72, v150
	s_nop 1
	v_cndmask_b32_e32 v32, v153, v151, vcc
	s_waitcnt vmcnt(63)
	v_mul_f32_e32 v150, v32, v152
	v_mul_f32_e32 v34, 0x42000000, v150
	v_and_b32_e32 v35, 0x7fffffff, v34
	v_cmp_nlt_f32_e64 s[72:73], |v34|, s2
	s_and_saveexec_b64 s[2:3], s[72:73]
	s_xor_b64 s[8:9], exec, s[2:3]
	s_cbranch_execz .LBB0_760
	v_lshrrev_b32_e32 v151, 23, v35
	v_add_u32_e32 v151, 0xffffff88, v151
	v_not_b32_e32 v152, 63
	v_cmp_lt_u32_e32 vcc, 63, v151
	s_mov_b32 s72, 0xfe5163ab
	v_mov_b32_e32 v155, 0
	v_cndmask_b32_e32 v152, 0, v152, vcc
	v_add_u32_e32 v151, v152, v151
	v_not_b32_e32 v152, 31
	v_cmp_lt_u32_e64 s[2:3], 31, v151
	s_nop 1
	v_cndmask_b32_e64 v153, 0, v152, s[2:3]
	v_add_u32_e32 v151, v153, v151
	v_cmp_lt_u32_e64 s[4:5], 31, v151
	s_nop 1
	v_cndmask_b32_e64 v152, 0, v152, s[4:5]
	v_add_u32_e32 v151, v152, v151
	v_and_b32_e32 v152, 0x7fffff, v35
	v_or_b32_e32 v166, 0x800000, v152
	v_mad_u64_u32 v[152:153], s[72:73], v166, s72, 0
	v_mov_b32_e32 v154, v153
	s_mov_b32 s72, 0x3c439041
	v_mad_u64_u32 v[156:157], s[72:73], v166, s72, v[154:155]
	v_mov_b32_e32 v154, v157
	s_mov_b32 s72, 0xdb629599
	v_mad_u64_u32 v[158:159], s[72:73], v166, s72, v[154:155]
	v_mov_b32_e32 v154, v159
	s_mov_b32 s72, 0xf534ddc0
	v_mad_u64_u32 v[160:161], s[72:73], v166, s72, v[154:155]
	v_mov_b32_e32 v154, v161
	s_mov_b32 s72, 0xfc2757d1
	v_mad_u64_u32 v[162:163], s[72:73], v166, s72, v[154:155]
	v_mov_b32_e32 v154, v163
	s_mov_b32 s72, 0x4e441529
	v_mad_u64_u32 v[164:165], s[72:73], v166, s72, v[154:155]
	v_mov_b32_e32 v154, v165
	s_mov_b32 s72, 0xa2f9836e
	v_mad_u64_u32 v[154:155], s[72:73], v166, s72, v[154:155]
	v_cndmask_b32_e32 v153, v164, v160, vcc
	v_cndmask_b32_e32 v154, v154, v162, vcc
	v_cndmask_b32_e32 v155, v155, v164, vcc
	v_cndmask_b32_e64 v157, v154, v153, s[2:3]
	v_cndmask_b32_e64 v154, v155, v154, s[2:3]
	v_cndmask_b32_e32 v155, v162, v158, vcc
	v_cndmask_b32_e64 v153, v153, v155, s[2:3]
	v_cndmask_b32_e64 v154, v154, v157, s[4:5]
	v_cndmask_b32_e64 v157, v157, v153, s[4:5]
	v_sub_u32_e32 v159, 32, v151
	v_alignbit_b32 v161, v154, v157, v159
	v_cmp_eq_u32_e64 s[6:7], 0, v151
	v_cndmask_b32_e32 v152, v158, v152, vcc
	s_mov_b32 s72, 0x3fc90fda
	v_cndmask_b32_e64 v151, v161, v154, s[6:7]
	v_cndmask_b32_e32 v154, v160, v156, vcc
	v_cndmask_b32_e64 v155, v155, v154, s[2:3]
	v_cndmask_b32_e64 v153, v153, v155, s[4:5]
	v_alignbit_b32 v156, v157, v153, v159
	v_cndmask_b32_e64 v156, v156, v157, s[6:7]
	v_bfe_u32 v161, v151, 29, 1
	v_cndmask_b32_e64 v152, v154, v152, s[2:3]
	v_alignbit_b32 v157, v151, v156, 30
	v_sub_u32_e32 v162, 0, v161
	v_cndmask_b32_e64 v152, v155, v152, s[4:5]
	v_xor_b32_e32 v157, v157, v162
	v_alignbit_b32 v154, v153, v152, v159
	v_cndmask_b32_e64 v153, v154, v153, s[6:7]
	v_ffbh_u32_e32 v155, v157
	v_alignbit_b32 v154, v156, v153, 30
	v_min_u32_e32 v155, 32, v155
	v_alignbit_b32 v152, v153, v152, 30
	v_xor_b32_e32 v154, v154, v162
	v_sub_u32_e32 v156, 31, v155
	v_xor_b32_e32 v152, v152, v162
	v_alignbit_b32 v157, v157, v154, v156
	v_alignbit_b32 v152, v154, v152, v156
	v_alignbit_b32 v153, v157, v152, 9
	v_ffbh_u32_e32 v154, v153
	v_min_u32_e32 v154, 32, v154
	v_lshrrev_b32_e32 v160, 29, v151
	v_not_b32_e32 v156, v154
	v_alignbit_b32 v152, v153, v152, v156
	v_lshlrev_b32_e32 v153, 31, v160
	v_or_b32_e32 v156, 0x33000000, v153
	v_add_lshl_u32 v154, v154, v155, 23
	v_lshrrev_b32_e32 v152, 9, v152
	v_sub_u32_e32 v154, v156, v154
	v_or_b32_e32 v153, 0.5, v153
	v_lshlrev_b32_e32 v155, 23, v155
	v_or_b32_e32 v152, v154, v152
	v_lshrrev_b32_e32 v154, 9, v157
	v_sub_u32_e32 v153, v153, v155
	v_or_b32_e32 v153, v154, v153
	v_mul_f32_e32 v154, 0x3fc90fda, v153
	v_fma_f32 v155, v153, s72, -v154
	v_fmamk_f32 v153, v153, 0x33a22168, v155
	v_fmac_f32_e32 v153, 0x3fc90fda, v152
	v_lshrrev_b32_e32 v151, 30, v151
	v_add_f32_e32 v36, v154, v153
	v_add_u32_e32 v38, v161, v151
; __device__ __forceinline__ void ssm_scan(LAS float* L, int item, const float* lam_re, const float* lam_im, const float* log_dt, const float* S, f16* X) {
;     ...
;     { const float er = expf((float)TC * lr * dt); float sn, cs; sincosf((float)TC * (li * dt), &sn, &cs); tr = er * cs; ti = er * sn; }
;     { const float er = expf((float)(33 * TC) * lr * dt); float sn, cs; sincosf((float)(33 * TC) * (li * dt), &sn, &cs); sr = er * cs; si = er * sn; }
.LBB0_760:
	s_andn2_saveexec_b64 s[2:3], s[8:9]
	s_cbranch_execz .LBB0_762
	s_mov_b32 s72, 0x3f22f983
	v_mul_f32_e64 v151, |v34|, s72
	v_rndne_f32_e32 v151, v151
	s_mov_b32 s72, 0xbfc90fda
	v_cvt_i32_f32_e32 v38, v151
	v_fma_f32 v152, v151, s72, |v34|
	v_fmamk_f32 v152, v151, 0xb3a22168, v152
	v_fmamk_f32 v36, v151, 0xa7c234c4, v152
.LBB0_762:
	s_or_b64 exec, exec, s[2:3]
	v_mul_f32_e32 v45, 0x44840000, v150
	s_brev_b32 s72, 18
	v_and_b32_e32 v51, 0x7fffffff, v45
	v_cmp_nlt_f32_e64 s[72:73], |v45|, s72
	s_and_saveexec_b64 s[2:3], s[72:73]
	s_xor_b64 s[8:9], exec, s[2:3]
	s_cbranch_execz .LBB0_764
	v_lshrrev_b32_e32 v150, 23, v51
	v_add_u32_e32 v150, 0xffffff88, v150
	v_not_b32_e32 v151, 63
	v_cmp_lt_u32_e32 vcc, 63, v150
	s_mov_b32 s72, 0xfe5163ab
	v_mov_b32_e32 v153, 0
	v_cndmask_b32_e32 v151, 0, v151, vcc
	v_add_u32_e32 v150, v151, v150
	v_not_b32_e32 v151, 31
	v_cmp_lt_u32_e64 s[2:3], 31, v150
	s_nop 1
	v_cndmask_b32_e64 v152, 0, v151, s[2:3]
	v_add_u32_e32 v150, v152, v150
	v_cmp_lt_u32_e64 s[4:5], 31, v150
	s_nop 1
	v_cndmask_b32_e64 v151, 0, v151, s[4:5]
	v_add_u32_e32 v164, v151, v150
	v_and_b32_e32 v150, 0x7fffff, v51
	v_or_b32_e32 v165, 0x800000, v150
	v_mad_u64_u32 v[150:151], s[72:73], v165, s72, 0
	v_mov_b32_e32 v152, v151
	s_mov_b32 s72, 0x3c439041
	v_mad_u64_u32 v[154:155], s[72:73], v165, s72, v[152:153]
	v_mov_b32_e32 v152, v155
	s_mov_b32 s72, 0xdb629599
	v_mad_u64_u32 v[156:157], s[72:73], v165, s72, v[152:153]
	v_mov_b32_e32 v152, v157
	s_mov_b32 s72, 0xf534ddc0
	v_mad_u64_u32 v[158:159], s[72:73], v165, s72, v[152:153]
	v_mov_b32_e32 v152, v159
	s_mov_b32 s72, 0xfc2757d1
	v_mad_u64_u32 v[160:161], s[72:73], v165, s72, v[152:153]
	v_mov_b32_e32 v152, v161
	s_mov_b32 s72, 0x4e441529
	v_mad_u64_u32 v[162:163], s[72:73], v165, s72, v[152:153]
	v_mov_b32_e32 v152, v163
	s_mov_b32 s72, 0xa2f9836e
	v_mad_u64_u32 v[152:153], s[72:73], v165, s72, v[152:153]
	v_cndmask_b32_e32 v151, v162, v158, vcc
	v_cndmask_b32_e32 v152, v152, v160, vcc
	v_cndmask_b32_e32 v153, v153, v162, vcc
	v_cndmask_b32_e64 v155, v152, v151, s[2:3]
	v_cndmask_b32_e64 v152, v153, v152, s[2:3]
	v_cndmask_b32_e32 v153, v160, v156, vcc
	v_cndmask_b32_e64 v151, v151, v153, s[2:3]
	v_cndmask_b32_e32 v154, v158, v154, vcc
	v_cndmask_b32_e64 v152, v152, v155, s[4:5]
	v_cndmask_b32_e64 v155, v155, v151, s[4:5]
	v_sub_u32_e32 v157, 32, v164
	v_cndmask_b32_e64 v153, v153, v154, s[2:3]
	v_alignbit_b32 v159, v152, v155, v157
	v_cmp_eq_u32_e64 s[6:7], 0, v164
	v_cndmask_b32_e64 v151, v151, v153, s[4:5]
	v_alignbit_b32 v158, v155, v151, v157
	v_cndmask_b32_e64 v152, v159, v152, s[6:7]
	v_cndmask_b32_e32 v150, v156, v150, vcc
	v_cndmask_b32_e64 v155, v158, v155, s[6:7]
	v_bfe_u32 v160, v152, 29, 1
	v_cndmask_b32_e64 v150, v154, v150, s[2:3]
	v_alignbit_b32 v158, v152, v155, 30
	v_sub_u32_e32 v161, 0, v160
	v_cndmask_b32_e64 v150, v153, v150, s[4:5]
	v_xor_b32_e32 v158, v158, v161
	v_alignbit_b32 v153, v151, v150, v157
	v_cndmask_b32_e64 v151, v153, v151, s[6:7]
	v_ffbh_u32_e32 v154, v158
	v_alignbit_b32 v153, v155, v151, 30
	v_min_u32_e32 v154, 32, v154
	v_alignbit_b32 v150, v151, v150, 30
	v_xor_b32_e32 v153, v153, v161
	v_sub_u32_e32 v155, 31, v154
	v_xor_b32_e32 v150, v150, v161
	v_alignbit_b32 v156, v158, v153, v155
	v_alignbit_b32 v150, v153, v150, v155
	v_alignbit_b32 v151, v156, v150, 9
	v_ffbh_u32_e32 v153, v151
	v_min_u32_e32 v153, 32, v153
	v_lshrrev_b32_e32 v159, 29, v152
	v_not_b32_e32 v155, v153
	v_alignbit_b32 v150, v151, v150, v155
	v_lshlrev_b32_e32 v151, 31, v159
	v_or_b32_e32 v155, 0x33000000, v151
	v_add_lshl_u32 v153, v153, v154, 23
	v_lshrrev_b32_e32 v150, 9, v150
	v_sub_u32_e32 v153, v155, v153
	v_or_b32_e32 v151, 0.5, v151
	v_lshlrev_b32_e32 v154, 23, v154
	v_or_b32_e32 v150, v153, v150
	v_lshrrev_b32_e32 v153, 9, v156
	v_sub_u32_e32 v151, v151, v154
	v_or_b32_e32 v151, v153, v151
	s_mov_b32 s72, 0x3fc90fda
	v_mul_f32_e32 v153, 0x3fc90fda, v151
	v_fma_f32 v154, v151, s72, -v153
	v_fmamk_f32 v151, v151, 0x33a22168, v154
	v_fmac_f32_e32 v151, 0x3fc90fda, v150
	v_lshrrev_b32_e32 v150, 30, v152
	v_add_f32_e32 v53, v153, v151
	v_add_u32_e32 v59, v160, v150
.LBB0_764:
	s_andn2_saveexec_b64 s[2:3], s[8:9]
	s_cbranch_execz .LBB0_766
	s_mov_b32 s72, 0x3f22f983
	v_mul_f32_e64 v150, |v45|, s72
	v_rndne_f32_e32 v150, v150
	s_mov_b32 s72, 0xbfc90fda
	v_cvt_i32_f32_e32 v59, v150
	v_fma_f32 v151, v150, s72, |v45|
	v_fmamk_f32 v151, v150, 0xb3a22168, v151
	v_fmamk_f32 v53, v150, 0xa7c234c4, v151
; __device__ __forceinline__ void ssm_scan(LAS float* L, int item, const float* lam_re, const float* lam_im, const float* log_dt, const float* S, f16* X) {
;     ...
;     { const float er = expf((float)TC * lr * dt); float sn, cs; sincosf((float)TC * (li * dt), &sn, &cs); tr = er * cs; ti = er * sn; }
;     { const float er = expf((float)(33 * TC) * lr * dt); float sn, cs; sincosf((float)(33 * TC) * (li * dt), &sn, &cs); sr = er * cs; si = er * sn; }
;     const float* Sg = S + (size_t)g * NCH * 256 + dir * 128 + n;
;     f16* Xg = X + (size_t)g * XGS + dir * 128 + n;
;     float vr[33], vi[33];
; #pragma unroll
;     for (int i = 0; i < 33; ++i) { const int p = seg * 33 + i;
;         const int row = p < 8 ? NLC + b * 8 + (dir == 0 ? p : 7 - p) : b * 256 + (dir == 0 ? p - 8 : 255 - (p - 8));
;         vr[i] = Sg[(size_t)row * 256]; vi[i] = Sg[(size_t)row * 256 + 64]; }
;     __builtin_amdgcn_sched_barrier(0);
;     float hr = 0.f, hi = 0.f;
; #pragma unroll
;     for (int i = 0; i < 33; ++i) { const float s_r = vr[i], s_i = vi[i]; vr[i] = hr; vi[i] = hi; const float nr = tr * hr - ti * hi + s_r, ni = tr * hi + ti * hr + s_i; hr = nr; hi = ni; }
.LBB0_766:
	s_or_b64 exec, exec, s[2:3]
	s_mov_b64 vcc, s[96:97]
	s_waitcnt vmcnt(62)
	v_mul_f32_e32 v2, 0x42000000, v30
	v_mul_f32_e32 v2, v32, v2
	s_mov_b32 s9, 0x3fb8aa3b
	v_mul_f32_e32 v4, 0x3fb8aa3b, v2
	v_fma_f32 v5, v2, s9, -v4
	v_rndne_f32_e32 v40, v4
	v_fmac_f32_e32 v5, 0x32a5705f, v2
	v_sub_f32_e32 v4, v4, v40
	v_add_f32_e32 v4, v4, v5
	v_exp_f32_e32 v4, v4
	v_cvt_i32_f32_e32 v5, v40
	s_mov_b32 s2, 0xc2ce8ed0
	v_cmp_ngt_f32_e32 vcc, s2, v2
	s_mov_b32 s4, 0x42b17218
	v_ldexp_f32 v4, v4, v5
	v_cndmask_b32_e32 v4, 0, v4, vcc
	v_mov_b32_e32 v77, 0x7f800000
	v_cmp_nlt_f32_e32 vcc, s4, v2
	v_mov_b32_e32 v71, 0x3c0881c4
	v_mov_b32_e32 v65, 0xbab64f3b
	v_cndmask_b32_e32 v2, v77, v4, vcc
	v_mul_f32_e32 v4, v36, v36
	v_fmamk_f32 v5, v4, 0xb94c1982, v71
	v_fmaak_f32 v5, v4, v5, 0xbe2aaa9d
	v_mul_f32_e32 v5, v4, v5
	v_fmac_f32_e32 v36, v36, v5
	v_fmamk_f32 v5, v4, 0x37d75334, v65
	v_fmaak_f32 v5, v4, v5, 0x3d2aabf7
	v_fmaak_f32 v5, v4, v5, 0xbf000004
	v_fma_f32 v4, v4, v5, 1.0
	v_lshlrev_b32_e32 v5, 30, v38
	v_and_b32_e32 v38, 1, v38
	v_cmp_eq_u32_e32 vcc, 0, v38
	v_xor_b32_e32 v35, v35, v34
	v_and_b32_e32 v5, 0x80000000, v5
	v_cndmask_b32_e32 v38, v4, v36, vcc
	v_xor_b32_e32 v36, 0x80000000, v36
	v_xor_b32_e32 v35, v35, v38
	v_cndmask_b32_e32 v4, v36, v4, vcc
	s_movk_i32 s3, 0x1f8
	v_xor_b32_e32 v35, v35, v5
	v_xor_b32_e32 v4, v4, v5
	v_mov_b32_e32 v61, 0x7fc00000
	v_cmp_class_f32_e64 vcc, v34, s3
	s_mov_b32 s8, 0x7f800000
	v_mov_b32_e32 v79, 0xbe2aaa9d
	v_cndmask_b32_e32 v5, v61, v35, vcc
	v_cndmask_b32_e32 v4, v61, v4, vcc
	v_pk_mul_f32 v[4:5], v[2:3], v[4:5] op_sel_hi:[0,1]
	v_mul_f32_e32 v2, 0x44840000, v30
	v_mul_f32_e32 v83, v32, v2
	v_mov_b32_e32 v67, 0x3d2aabf7
	v_mov_b32_e32 v73, 0xbf000004
	v_cmp_ngt_f32_e64 s[2:3], s2, v83
	v_cmp_nlt_f32_e64 s[4:5], s4, v83
	v_pk_mul_f32 v[106:107], v[4:5], 0 op_sel_hi:[1,0]
	v_cmp_lt_i32_e32 vcc, 0, v39
	v_pk_fma_f32 v[34:35], v[4:5], 0, v[106:107] op_sel:[0,0,1] op_sel_hi:[1,0,1] neg_lo:[0,0,1] neg_hi:[0,0,1]
	v_pk_fma_f32 v[40:41], v[4:5], 0, v[106:107] op_sel_hi:[1,0,0]
	s_nop 0
	v_mov_b32_e32 v35, v41
	v_pk_add_f32 v[104:105], v[34:35], v[8:9]
	s_nop 0
	v_pk_mul_f32 v[8:9], v[4:5], v[104:105]
	s_nop 0
	v_sub_f32_e32 v2, v8, v9
	v_pk_mul_f32 v[8:9], v[4:5], v[104:105] op_sel:[1,0] op_sel_hi:[0,1]
	v_add_f32_e32 v100, v42, v2
	v_add_f32_e32 v2, v8, v9
	v_add_f32_e32 v102, v44, v2
	s_waitcnt vmcnt(27)
	v_pk_mul_f32 v[8:9], v[4:5], v[102:103] op_sel:[1,0] op_sel_hi:[0,0]
	v_pk_fma_f32 v[34:35], v[4:5], v[100:101], v[8:9] neg_lo:[0,0,1] neg_hi:[0,0,1]
	v_pk_fma_f32 v[8:9], v[4:5], v[100:101], v[8:9] op_sel_hi:[1,0,1]
	s_nop 0
	v_mov_b32_e32 v35, v9
	v_pk_add_f32 v[98:99], v[6:7], v[34:35]
	s_nop 0
	v_pk_mul_f32 v[6:7], v[4:5], v[98:99]
	s_nop 0
	v_sub_f32_e32 v2, v6, v7
	v_pk_mul_f32 v[6:7], v[4:5], v[98:99] op_sel:[0,1] op_sel_hi:[1,0]
	v_add_f32_e32 v94, v50, v2
	v_add_f32_e32 v2, v6, v7
	v_add_f32_e32 v96, v52, v2
	v_pk_mul_f32 v[6:7], v[4:5], v[96:97] op_sel:[1,0] op_sel_hi:[0,0]
	v_pk_fma_f32 v[8:9], v[4:5], v[94:95], v[6:7] neg_lo:[0,0,1] neg_hi:[0,0,1]
	v_pk_fma_f32 v[6:7], v[4:5], v[94:95], v[6:7] op_sel_hi:[1,0,1]
	s_nop 0
	v_mov_b32_e32 v9, v7
	v_pk_add_f32 v[92:93], v[12:13], v[8:9]
	s_nop 0
	v_pk_mul_f32 v[6:7], v[4:5], v[92:93]
	s_nop 0
	v_sub_f32_e32 v2, v6, v7
	v_pk_mul_f32 v[6:7], v[4:5], v[92:93] op_sel:[0,1] op_sel_hi:[1,0]
	v_add_f32_e32 v88, v58, v2
	v_add_f32_e32 v2, v6, v7
	v_add_f32_e32 v90, v62, v2
	v_pk_mul_f32 v[6:7], v[4:5], v[90:91] op_sel:[1,0] op_sel_hi:[0,0]
	v_pk_fma_f32 v[8:9], v[4:5], v[88:89], v[6:7] neg_lo:[0,0,1] neg_hi:[0,0,1]
	v_pk_fma_f32 v[6:7], v[4:5], v[88:89], v[6:7] op_sel_hi:[1,0,1]
	s_nop 0
	v_mov_b32_e32 v9, v7
	v_pk_add_f32 v[86:87], v[10:11], v[8:9]
	s_nop 0
	v_pk_mul_f32 v[6:7], v[4:5], v[86:87]
	s_nop 0
	v_sub_f32_e32 v2, v6, v7
	v_pk_mul_f32 v[6:7], v[4:5], v[86:87] op_sel:[0,1] op_sel_hi:[1,0]
	v_add_f32_e32 v82, v63, v2
	v_add_f32_e32 v2, v6, v7
	v_add_f32_e32 v84, v64, v2
	v_pk_mul_f32 v[6:7], v[4:5], v[84:85] op_sel:[1,0] op_sel_hi:[0,0]
	v_pk_fma_f32 v[8:9], v[4:5], v[82:83], v[6:7] neg_lo:[0,0,1] neg_hi:[0,0,1]
	v_pk_fma_f32 v[6:7], v[4:5], v[82:83], v[6:7] op_sel_hi:[1,0,1]
	s_nop 0
	v_mov_b32_e32 v9, v7
	v_pk_add_f32 v[80:81], v[16:17], v[8:9]
	s_nop 0
	v_pk_mul_f32 v[6:7], v[4:5], v[80:81]
	s_nop 0
	v_sub_f32_e32 v2, v6, v7
	v_pk_mul_f32 v[6:7], v[4:5], v[80:81] op_sel:[0,1] op_sel_hi:[1,0]
	v_add_f32_e32 v76, v66, v2
	v_add_f32_e32 v2, v6, v7
	v_add_f32_e32 v78, v68, v2
	v_pk_mul_f32 v[6:7], v[4:5], v[78:79] op_sel:[1,0] op_sel_hi:[0,0]
	v_pk_fma_f32 v[8:9], v[4:5], v[76:77], v[6:7] neg_lo:[0,0,1] neg_hi:[0,0,1]
	v_pk_fma_f32 v[6:7], v[4:5], v[76:77], v[6:7] op_sel_hi:[1,0,1]
	s_nop 0
	v_mov_b32_e32 v9, v7
	v_pk_add_f32 v[74:75], v[14:15], v[8:9]
	s_nop 0
	v_pk_mul_f32 v[6:7], v[4:5], v[74:75]
	s_nop 0
	v_sub_f32_e32 v2, v6, v7
	v_pk_mul_f32 v[6:7], v[4:5], v[74:75] op_sel:[0,1] op_sel_hi:[1,0]
	v_add_f32_e32 v70, v69, v2
	v_add_f32_e32 v2, v6, v7
	v_add_f32_e32 v72, v72, v2
	v_pk_mul_f32 v[6:7], v[4:5], v[72:73] op_sel:[1,0] op_sel_hi:[0,0]
	v_pk_fma_f32 v[8:9], v[4:5], v[70:71], v[6:7] neg_lo:[0,0,1] neg_hi:[0,0,1]
	v_pk_fma_f32 v[6:7], v[4:5], v[70:71], v[6:7] op_sel_hi:[1,0,1]
	s_nop 0
	v_mov_b32_e32 v9, v7
	v_pk_add_f32 v[68:69], v[20:21], v[8:9]
	s_nop 0
	v_pk_mul_f32 v[6:7], v[4:5], v[68:69]
	s_nop 0
	v_sub_f32_e32 v2, v6, v7
	v_pk_mul_f32 v[6:7], v[4:5], v[68:69] op_sel:[0,1] op_sel_hi:[1,0]
	v_add_f32_e32 v64, v85, v2
	v_add_f32_e32 v2, v6, v7
	v_add_f32_e32 v66, v89, v2
	v_pk_mul_f32 v[6:7], v[4:5], v[66:67] op_sel:[1,0] op_sel_hi:[0,0]
	v_pk_fma_f32 v[8:9], v[4:5], v[64:65], v[6:7] neg_lo:[0,0,1] neg_hi:[0,0,1]
	v_pk_fma_f32 v[6:7], v[4:5], v[64:65], v[6:7] op_sel_hi:[1,0,1]
	s_nop 0
	v_mov_b32_e32 v9, v7
	v_pk_add_f32 v[62:63], v[18:19], v[8:9]
	s_nop 0
	v_pk_mul_f32 v[6:7], v[4:5], v[62:63]
	s_nop 0
	v_sub_f32_e32 v2, v6, v7
	v_pk_mul_f32 v[6:7], v[4:5], v[62:63] op_sel:[0,1] op_sel_hi:[1,0]
	v_add_f32_e32 v58, v91, v2
	v_add_f32_e32 v2, v6, v7
	v_add_f32_e32 v60, v95, v2
	v_pk_mul_f32 v[6:7], v[4:5], v[60:61] op_sel:[1,0] op_sel_hi:[0,0]
	v_pk_fma_f32 v[8:9], v[4:5], v[58:59], v[6:7] neg_lo:[0,0,1] neg_hi:[0,0,1]
	v_pk_fma_f32 v[6:7], v[4:5], v[58:59], v[6:7] op_sel_hi:[1,0,1]
	s_nop 0
	v_mov_b32_e32 v9, v7
	v_pk_add_f32 v[56:57], v[24:25], v[8:9]
	s_nop 0
	v_pk_mul_f32 v[6:7], v[4:5], v[56:57]
	s_nop 0
	v_sub_f32_e32 v2, v6, v7
	v_pk_mul_f32 v[6:7], v[4:5], v[56:57] op_sel:[0,1] op_sel_hi:[1,0]
	v_add_f32_e32 v50, v97, v2
	v_add_f32_e32 v2, v6, v7
	v_add_f32_e32 v52, v101, v2
	v_pk_mul_f32 v[6:7], v[4:5], v[52:53] op_sel:[1,0] op_sel_hi:[0,0]
	v_pk_fma_f32 v[8:9], v[4:5], v[50:51], v[6:7] neg_lo:[0,0,1] neg_hi:[0,0,1]
	v_pk_fma_f32 v[6:7], v[4:5], v[50:51], v[6:7] op_sel_hi:[1,0,1]
	s_nop 0
	v_mov_b32_e32 v9, v7
	v_pk_add_f32 v[46:47], v[22:23], v[8:9]
	s_nop 0
	v_pk_mul_f32 v[6:7], v[4:5], v[46:47]
	s_nop 0
	v_sub_f32_e32 v2, v6, v7
	v_pk_mul_f32 v[6:7], v[4:5], v[46:47] op_sel:[0,1] op_sel_hi:[1,0]
	v_add_f32_e32 v42, v103, v2
	v_add_f32_e32 v2, v6, v7
	s_waitcnt vmcnt(26)
; __device__ __forceinline__ void ssm_scan(LAS float* L, int item, const float* lam_re, const float* lam_im, const float* log_dt, const float* S, f16* X) {
;     ...
;     for (int i = 0; i < 33; ++i) { const float s_r = vr[i], s_i = vi[i]; vr[i] = hr; vi[i] = hi; const float nr = tr * hr - ti * hi + s_r, ni = tr * hi + ti * hr + s_i; hr = nr; hi = ni; }
;     L[(seg * 64 + n) * 2] = hr; L[(seg * 64 + n) * 2 + 1] = hi;
;     __syncthreads();
;     float ir = 0.f, ii = 0.f;
;     for (int k = 0; k < seg; ++k) { const float er = L[(k * 64 + n) * 2], ei = L[(k * 64 + n) * 2 + 1]; const float nr = sr * ir - si * ii + er, ni = sr * ii + si * ir + ei; ir = nr; ii = ni; }
	v_add_f32_e32 v44, v114, v2
	v_pk_mul_f32 v[6:7], v[4:5], v[44:45] op_sel:[1,0] op_sel_hi:[0,0]
	v_pk_fma_f32 v[8:9], v[4:5], v[42:43], v[6:7] neg_lo:[0,0,1] neg_hi:[0,0,1]
	v_pk_fma_f32 v[6:7], v[4:5], v[42:43], v[6:7] op_sel_hi:[1,0,1]
	s_nop 0
	v_mov_b32_e32 v9, v7
	s_waitcnt vmcnt(24)
	v_pk_add_f32 v[40:41], v[28:29], v[8:9]
	s_nop 0
	v_pk_mul_f32 v[6:7], v[4:5], v[40:41]
	s_nop 0
	v_sub_f32_e32 v2, v6, v7
	v_pk_mul_f32 v[6:7], v[4:5], v[40:41] op_sel:[0,1] op_sel_hi:[1,0]
	s_waitcnt vmcnt(23)
	v_add_f32_e32 v36, v115, v2
	v_add_f32_e32 v2, v6, v7
	s_waitcnt vmcnt(22)
	v_add_f32_e32 v38, v116, v2
	v_pk_mul_f32 v[6:7], v[4:5], v[38:39] op_sel:[1,0] op_sel_hi:[0,0]
	v_pk_fma_f32 v[8:9], v[4:5], v[36:37], v[6:7] neg_lo:[0,0,1] neg_hi:[0,0,1]
	v_pk_fma_f32 v[6:7], v[4:5], v[36:37], v[6:7] op_sel_hi:[1,0,1]
	s_nop 0
	v_mov_b32_e32 v9, v7
	s_waitcnt vmcnt(20)
	v_pk_add_f32 v[34:35], v[26:27], v[8:9]
	s_nop 0
	v_pk_mul_f32 v[6:7], v[4:5], v[34:35]
	s_nop 0
	v_sub_f32_e32 v2, v6, v7
	v_pk_mul_f32 v[6:7], v[4:5], v[34:35] op_sel:[0,1] op_sel_hi:[1,0]
	s_waitcnt vmcnt(19)
	v_add_f32_e32 v30, v117, v2
	v_add_f32_e32 v2, v6, v7
	s_waitcnt vmcnt(18)
	v_add_f32_e32 v32, v118, v2
	v_pk_mul_f32 v[6:7], v[4:5], v[32:33] op_sel:[1,0] op_sel_hi:[0,0]
	v_pk_fma_f32 v[8:9], v[4:5], v[30:31], v[6:7] neg_lo:[0,0,1] neg_hi:[0,0,1]
	v_pk_fma_f32 v[6:7], v[4:5], v[30:31], v[6:7] op_sel_hi:[1,0,1]
	s_nop 0
	v_mov_b32_e32 v9, v7
	s_waitcnt vmcnt(16)
	v_pk_add_f32 v[28:29], v[54:55], v[8:9]
	s_nop 0
	v_pk_mul_f32 v[6:7], v[4:5], v[28:29]
	s_nop 0
	v_sub_f32_e32 v2, v6, v7
	v_pk_mul_f32 v[6:7], v[4:5], v[28:29] op_sel:[0,1] op_sel_hi:[1,0]
	s_waitcnt vmcnt(15)
	v_add_f32_e32 v24, v119, v2
	v_add_f32_e32 v2, v6, v7
	s_waitcnt vmcnt(14)
	v_add_f32_e32 v26, v120, v2
	v_pk_mul_f32 v[6:7], v[4:5], v[26:27] op_sel:[1,0] op_sel_hi:[0,0]
	v_pk_fma_f32 v[8:9], v[4:5], v[24:25], v[6:7] neg_lo:[0,0,1] neg_hi:[0,0,1]
	v_pk_fma_f32 v[6:7], v[4:5], v[24:25], v[6:7] op_sel_hi:[1,0,1]
	s_nop 0
	v_mov_b32_e32 v9, v7
	s_waitcnt vmcnt(12)
	v_pk_add_f32 v[22:23], v[48:49], v[8:9]
	s_nop 0
	v_pk_mul_f32 v[6:7], v[4:5], v[22:23]
	s_nop 0
	v_sub_f32_e32 v2, v6, v7
	v_pk_mul_f32 v[6:7], v[4:5], v[22:23] op_sel:[0,1] op_sel_hi:[1,0]
	s_waitcnt vmcnt(11)
	v_add_f32_e32 v18, v121, v2
	v_add_f32_e32 v2, v6, v7
	s_waitcnt vmcnt(10)
	v_add_f32_e32 v20, v122, v2
	v_pk_mul_f32 v[6:7], v[4:5], v[20:21] op_sel:[1,0] op_sel_hi:[0,0]
	v_pk_fma_f32 v[8:9], v[4:5], v[18:19], v[6:7] neg_lo:[0,0,1] neg_hi:[0,0,1]
	v_pk_fma_f32 v[6:7], v[4:5], v[18:19], v[6:7] op_sel_hi:[1,0,1]
	s_nop 0
	v_mov_b32_e32 v9, v7
	s_waitcnt vmcnt(8)
	v_pk_add_f32 v[16:17], v[112:113], v[8:9]
	s_nop 0
	v_pk_mul_f32 v[6:7], v[4:5], v[16:17]
	s_nop 0
	v_sub_f32_e32 v2, v6, v7
	v_pk_mul_f32 v[6:7], v[4:5], v[16:17] op_sel:[0,1] op_sel_hi:[1,0]
	s_waitcnt vmcnt(7)
	v_add_f32_e32 v12, v123, v2
	v_add_f32_e32 v2, v6, v7
	s_waitcnt vmcnt(6)
	v_add_f32_e32 v14, v124, v2
	v_pk_mul_f32 v[6:7], v[4:5], v[14:15] op_sel:[1,0] op_sel_hi:[0,0]
	v_pk_fma_f32 v[8:9], v[4:5], v[12:13], v[6:7] neg_lo:[0,0,1] neg_hi:[0,0,1]
	v_pk_fma_f32 v[6:7], v[4:5], v[12:13], v[6:7] op_sel_hi:[1,0,1]
	s_nop 0
	v_mov_b32_e32 v9, v7
	s_waitcnt vmcnt(4)
	v_pk_add_f32 v[10:11], v[110:111], v[8:9]
	s_nop 0
	v_pk_mul_f32 v[6:7], v[4:5], v[10:11]
	v_pk_mul_f32 v[8:9], v[4:5], v[10:11] op_sel:[0,1] op_sel_hi:[1,0]
	v_sub_f32_e32 v2, v6, v7
	s_waitcnt vmcnt(3)
	v_add_f32_e32 v6, v125, v2
	v_add_f32_e32 v2, v8, v9
	s_waitcnt vmcnt(2)
	v_add_f32_e32 v8, v126, v2
	v_pk_mul_f32 v[48:49], v[4:5], v[8:9] op_sel:[1,0] op_sel_hi:[0,0]
	v_pk_fma_f32 v[54:55], v[4:5], v[6:7], v[48:49] neg_lo:[0,0,1] neg_hi:[0,0,1]
	v_pk_fma_f32 v[48:49], v[4:5], v[6:7], v[48:49] op_sel_hi:[1,0,1]
	v_lshl_add_u32 v2, v37, 3, 0
	v_mov_b32_e32 v55, v49
	s_waitcnt vmcnt(0)
	v_pk_add_f32 v[48:49], v[108:109], v[54:55]
	ds_write_b64 v2, v[48:49]
	v_mov_b32_e32 v2, v3
	s_waitcnt lgkmcnt(0)
	s_barrier
	s_and_saveexec_b64 s[6:7], vcc
	s_cbranch_execz .LBB0_776
	v_mul_f32_e32 v2, 0x3fb8aa3b, v83
	v_fma_f32 v3, v83, s9, -v2
	v_rndne_f32_e32 v7, v2
	v_fmac_f32_e32 v3, 0x32a5705f, v83
	v_sub_f32_e32 v2, v2, v7
	v_add_f32_e32 v2, v2, v3
	v_cvt_i32_f32_e32 v3, v7
	v_exp_f32_e32 v2, v2
	v_and_b32_e32 v15, 1, v59
	v_xor_b32_e32 v19, v51, v45
	v_and_b32_e32 v9, 0x7fffffff, v45
	v_ldexp_f32 v2, v2, v3
	v_mul_f32_e32 v3, v53, v53
	v_fmac_f32_e32 v71, 0xb94c1982, v3
	v_fmac_f32_e32 v65, 0x37d75334, v3
	v_fmac_f32_e32 v79, v3, v71
	v_fmac_f32_e32 v67, v3, v65
	v_mul_f32_e32 v7, v3, v79
	v_fmac_f32_e32 v73, v3, v67
	v_cndmask_b32_e64 v2, 0, v2, s[2:3]
	v_fmac_f32_e32 v53, v53, v7
	v_fma_f32 v3, v3, v73, 1.0
	v_cmp_eq_u32_e64 s[2:3], 0, v15
	v_lshlrev_b32_e32 v7, 30, v59
	v_and_b32_e32 v13, 0x80000000, v7
	v_cndmask_b32_e64 v15, v3, v53, s[2:3]
	v_xor_b32_e32 v15, v19, v15
	v_xor_b32_e32 v19, 0x80000000, v53
	v_cndmask_b32_e64 v3, v19, v3, s[2:3]
	v_xor_b32_e32 v15, v15, v13
	v_xor_b32_e32 v3, v3, v13
	v_cmp_lg_f32_e64 s[2:3], s8, v9
	v_cndmask_b32_e64 v2, v77, v2, s[4:5]
	v_mov_b32_e32 v7, 0
	v_cndmask_b32_e64 v49, v61, v15, s[2:3]
	v_cndmask_b32_e64 v48, v61, v3, s[2:3]
	v_pk_mul_f32 v[48:49], v[2:3], v[48:49] op_sel_hi:[0,1]
	v_lshlrev_b32_e32 v9, 3, v33
	v_cmp_lt_u32_e64 s[2:3], 7, v39
	v_mov_b32_e32 v108, 0
	v_mov_b32_e32 v2, 0
	s_and_saveexec_b64 s[4:5], s[2:3]
	s_cbranch_execz .LBB0_771
	s_mov_b32 s18, 0
	v_add_u32_e32 v13, 0, v9
	v_and_b32_e32 v7, 0x7ffffff8, v39
	v_pk_mov_b32 v[54:55], v[48:49], v[48:49] op_sel:[1,0]
	v_mov_b32_e32 v2, 0
	s_mov_b64 s[8:9], 0
	v_mov_b32_e32 v108, 0

; #define MFMA16(a, b, c) __builtin_amdgcn_mfma_f32_16x16x32_bf16(a, b, c, 0, 0, 0)
; #define MFMA16(a, b, c) __builtin_amdgcn_mfma_f32_16x16x32_f16(a, b, c, 0, 0, 0)
; __device__ __forceinline__ void ctxs_item(int g, const f16* X, const f16* PG, float* S) {
;     const int tid = threadIdx.x, wave = tid >> 6, lane = tid & 63, fr = lane & 15, fq = lane >> 4;
;     const f16* ap = X + (size_t)g * XGS + (size_t)(NLC + fr) * XK + 256 + 8 * fq;
;     const f16* bp = PG + (size_t)g * PGS + (size_t)(32 * wave + fr) * 512 + 8 * fq;
;     f32x4 d0 = {0.f, 0.f, 0.f, 0.f}, d1 = d0;
; #pragma unroll 1
;     for (int kb = 0; kb < 16; kb += 8) { f16x8 av[8], b0[8], b1[8];
; #pragma unroll
;         for (int k = 0; k < 8; ++k) { av[k] = *(const f16x8*)(ap + (kb + k) * 32); b0[k] = *(const f16x8*)(bp + (kb + k) * 32); b1[k] = *(const f16x8*)(bp + 16 * 512 + (kb + k) * 32); }
;         __builtin_amdgcn_sched_barrier(0);
; #pragma unroll
;         for (int k = 0; k < 8; ++k) { d0 = MFMA16(av[k], b0[k], d0); d1 = MFMA16(av[k], b1[k], d1); } }
.LBB0_841:
	s_lshl_b64 s[6:7], s[2:3], 1
	s_or_b32 s10, s2, 32
	s_or_b32 s12, s2, 64
	s_or_b32 s14, s2, 0x60
	s_or_b32 s18, s2, 0x80
	s_or_b32 s20, s2, 0xa0
	s_mov_b32 s11, s3
	s_mov_b32 s13, s3
	s_mov_b32 s15, s3
	s_mov_b32 s19, s3
	s_mov_b32 s21, s3
	v_lshl_add_u64 v[96:97], v[12:13], 0, s[6:7]
	v_lshl_add_u64 v[104:105], v[14:15], 0, s[6:7]
	v_lshl_add_u64 v[36:37], v[16:17], 0, s[6:7]
	v_lshl_add_u64 v[40:41], s[10:11], 1, v[16:17]
	v_lshl_add_u64 v[60:61], s[12:13], 1, v[16:17]
	v_lshl_add_u64 v[64:65], s[14:15], 1, v[16:17]
	v_lshl_add_u64 v[84:85], s[18:19], 1, v[16:17]
	v_lshl_add_u64 v[88:89], s[20:21], 1, v[16:17]
	s_or_b32 s36, s2, 0xc0
	s_or_b32 s2, s2, 0xe0
	global_load_dwordx4 v[20:23], v[96:97], off
	global_load_dwordx4 v[24:27], v[96:97], off offset:64
	global_load_dwordx4 v[28:31], v[104:105], off
	global_load_dwordx4 v[32:35], v[104:105], off offset:64
	s_nop 0
	global_load_dwordx4 v[36:39], v[36:37], off
	s_nop 0
	global_load_dwordx4 v[40:43], v[40:41], off
	s_nop 0
	global_load_dwordx4 v[44:47], v[96:97], off offset:128
	global_load_dwordx4 v[48:51], v[96:97], off offset:192
	global_load_dwordx4 v[52:55], v[104:105], off offset:128
	global_load_dwordx4 v[56:59], v[104:105], off offset:192
	s_nop 0
	global_load_dwordx4 v[60:63], v[60:61], off
	s_nop 0
	global_load_dwordx4 v[64:67], v[64:65], off
	s_nop 0
	global_load_dwordx4 v[68:71], v[96:97], off offset:256
	global_load_dwordx4 v[72:75], v[96:97], off offset:320
	global_load_dwordx4 v[76:79], v[104:105], off offset:256
	global_load_dwordx4 v[80:83], v[104:105], off offset:320
	s_nop 0
	global_load_dwordx4 v[84:87], v[84:85], off
	s_nop 0
	global_load_dwordx4 v[88:91], v[88:89], off
	s_mov_b32 s37, s3
	global_load_dwordx4 v[92:95], v[96:97], off offset:384
	s_nop 0
	global_load_dwordx4 v[96:99], v[96:97], off offset:448
	s_nop 0
	global_load_dwordx4 v[100:103], v[104:105], off offset:384
	s_nop 0
	global_load_dwordx4 v[104:107], v[104:105], off offset:448
	v_lshl_add_u64 v[108:109], s[36:37], 1, v[16:17]
	v_lshl_add_u64 v[112:113], s[2:3], 1, v[16:17]
	global_load_dwordx4 v[108:111], v[108:109], off
	s_nop 0
	global_load_dwordx4 v[112:115], v[112:113], off
	s_movk_i32 s2, 0x100
	s_lshl_b64 s[6:7], s[2:3], 1
	s_or_b32 s10, s2, 32
	s_or_b32 s12, s2, 64
	s_or_b32 s14, s2, 0x60
	s_or_b32 s18, s2, 0x80
	s_or_b32 s20, s2, 0xa0
	s_mov_b32 s11, s3
	s_mov_b32 s13, s3
	s_mov_b32 s15, s3
	s_mov_b32 s19, s3
	s_mov_b32 s21, s3
	v_lshl_add_u64 v[196:197], v[12:13], 0, s[6:7]
	v_lshl_add_u64 v[204:205], v[14:15], 0, s[6:7]
	v_lshl_add_u64 v[132:133], v[16:17], 0, s[6:7]
	v_lshl_add_u64 v[136:137], s[10:11], 1, v[16:17]
	v_lshl_add_u64 v[160:161], s[12:13], 1, v[16:17]
	v_lshl_add_u64 v[164:165], s[14:15], 1, v[16:17]
	v_lshl_add_u64 v[184:185], s[18:19], 1, v[16:17]
	v_lshl_add_u64 v[188:189], s[20:21], 1, v[16:17]
	s_or_b32 s36, s2, 0xc0
	s_or_b32 s2, s2, 0xe0
	global_load_dwordx4 v[116:119], v[196:197], off
	global_load_dwordx4 v[120:123], v[196:197], off offset:64
	global_load_dwordx4 v[124:127], v[204:205], off
	global_load_dwordx4 v[128:131], v[204:205], off offset:64
	s_nop 0
	global_load_dwordx4 v[132:135], v[132:133], off
	s_nop 0
	global_load_dwordx4 v[136:139], v[136:137], off
	s_nop 0
	global_load_dwordx4 v[144:147], v[196:197], off offset:128
	global_load_dwordx4 v[148:151], v[196:197], off offset:192
	global_load_dwordx4 v[152:155], v[204:205], off offset:128
	global_load_dwordx4 v[156:159], v[204:205], off offset:192
	s_nop 0
	global_load_dwordx4 v[160:163], v[160:161], off
	s_nop 0
	global_load_dwordx4 v[164:167], v[164:165], off
	s_nop 0
	global_load_dwordx4 v[168:171], v[196:197], off offset:256
	global_load_dwordx4 v[172:175], v[196:197], off offset:320
	global_load_dwordx4 v[176:179], v[204:205], off offset:256
	global_load_dwordx4 v[180:183], v[204:205], off offset:320
	s_nop 0
	global_load_dwordx4 v[184:187], v[184:185], off
	s_nop 0
	global_load_dwordx4 v[188:191], v[188:189], off
	s_mov_b32 s37, s3
	global_load_dwordx4 v[192:195], v[196:197], off offset:384
	s_nop 0
	global_load_dwordx4 v[196:199], v[196:197], off offset:448
	s_nop 0
	global_load_dwordx4 v[200:203], v[204:205], off offset:384
	s_nop 0
	global_load_dwordx4 v[204:207], v[204:205], off offset:448
	v_lshl_add_u64 v[208:209], s[36:37], 1, v[16:17]
	v_lshl_add_u64 v[220:221], s[2:3], 1, v[16:17]
	global_load_dwordx4 v[208:211], v[208:209], off
	s_nop 0
	global_load_dwordx4 v[220:223], v[220:221], off
	s_waitcnt vmcnt(24)
; #define MFMA16(a, b, c) __builtin_amdgcn_mfma_f32_16x16x32_bf16(a, b, c, 0, 0, 0)
; #define MFMA16(a, b, c) __builtin_amdgcn_mfma_f32_16x16x32_f16(a, b, c, 0, 0, 0)
; __device__ __forceinline__ void st_wt_f32(void* p, float v) { asm volatile("global_store_dword %0, %1, off sc0 sc1" :: "v"(p), "v"(v) : "memory"); }
; __device__ __forceinline__ void ctxs_item(int g, const f16* X, const f16* PG, float* S) {
;     ...
;     for (int kb = 0; kb < 16; kb += 8) { f16x8 av[8], b0[8], b1[8];
; #pragma unroll
;         for (int k = 0; k < 8; ++k) { av[k] = *(const f16x8*)(ap + (kb + k) * 32); b0[k] = *(const f16x8*)(bp + (kb + k) * 32); b1[k] = *(const f16x8*)(bp + 16 * 512 + (kb + k) * 32); }
;         __builtin_amdgcn_sched_barrier(0);
; #pragma unroll
;         for (int k = 0; k < 8; ++k) { d0 = MFMA16(av[k], b0[k], d0); d1 = MFMA16(av[k], b1[k], d1); } }
;     float* sp = S + ((size_t)g * NCH + NLC + 4 * fq) * 256 + 32 * wave + fr;
; #pragma unroll
;     for (int r = 0; r < 4; ++r) { if (wave < 4) { sp[(size_t)r * 256] = d0[r]; sp[(size_t)r * 256 + 16] = d1[r]; } else { st_wt_f32(sp + (size_t)r * 256, d0[r]); st_wt_f32(sp + (size_t)r * 256 + 16, d1[r]); } }
	v_mfma_f32_16x16x32_bf16 v[2:5], v[20:23], v[28:31], v[2:5]
	v_mfma_f32_16x16x32_bf16 v[6:9], v[20:23], v[36:39], v[6:9]
	v_mfma_f32_16x16x32_bf16 v[2:5], v[24:27], v[32:35], v[2:5]
	v_mfma_f32_16x16x32_bf16 v[6:9], v[24:27], v[40:43], v[6:9]
	v_mfma_f32_16x16x32_bf16 v[2:5], v[44:47], v[52:55], v[2:5]
	v_mfma_f32_16x16x32_bf16 v[6:9], v[44:47], v[60:63], v[6:9]
	v_mfma_f32_16x16x32_bf16 v[2:5], v[48:51], v[56:59], v[2:5]
	v_mfma_f32_16x16x32_bf16 v[6:9], v[48:51], v[64:67], v[6:9]
	v_mfma_f32_16x16x32_bf16 v[2:5], v[68:71], v[76:79], v[2:5]
	v_mfma_f32_16x16x32_bf16 v[6:9], v[68:71], v[84:87], v[6:9]
	v_mfma_f32_16x16x32_bf16 v[2:5], v[72:75], v[80:83], v[2:5]
	v_mfma_f32_16x16x32_bf16 v[6:9], v[72:75], v[88:91], v[6:9]
	v_mfma_f32_16x16x32_bf16 v[2:5], v[92:95], v[100:103], v[2:5]
	v_mfma_f32_16x16x32_bf16 v[6:9], v[92:95], v[108:111], v[6:9]
	v_mfma_f32_16x16x32_bf16 v[2:5], v[96:99], v[104:107], v[2:5]
	v_mfma_f32_16x16x32_bf16 v[6:9], v[96:99], v[112:115], v[6:9]
	s_waitcnt vmcnt(0)
	v_mfma_f32_16x16x32_bf16 v[2:5], v[116:119], v[124:127], v[2:5]
	v_mfma_f32_16x16x32_bf16 v[6:9], v[116:119], v[132:135], v[6:9]
	v_mfma_f32_16x16x32_bf16 v[2:5], v[120:123], v[128:131], v[2:5]
	v_mfma_f32_16x16x32_bf16 v[6:9], v[120:123], v[136:139], v[6:9]
	v_mfma_f32_16x16x32_bf16 v[2:5], v[144:147], v[152:155], v[2:5]
	v_mfma_f32_16x16x32_bf16 v[6:9], v[144:147], v[160:163], v[6:9]
	v_mfma_f32_16x16x32_bf16 v[2:5], v[148:151], v[156:159], v[2:5]
	v_mfma_f32_16x16x32_bf16 v[6:9], v[148:151], v[164:167], v[6:9]
	v_mfma_f32_16x16x32_bf16 v[2:5], v[168:171], v[176:179], v[2:5]
	v_mfma_f32_16x16x32_bf16 v[6:9], v[168:171], v[184:187], v[6:9]
	v_mfma_f32_16x16x32_bf16 v[2:5], v[172:175], v[180:183], v[2:5]
	v_mfma_f32_16x16x32_bf16 v[6:9], v[172:175], v[188:191], v[6:9]
	v_mfma_f32_16x16x32_bf16 v[2:5], v[192:195], v[200:203], v[2:5]
	v_mfma_f32_16x16x32_bf16 v[6:9], v[192:195], v[208:211], v[6:9]
	v_mfma_f32_16x16x32_bf16 v[2:5], v[196:199], v[204:207], v[2:5]
	v_mfma_f32_16x16x32_bf16 v[6:9], v[196:199], v[220:223], v[6:9]
	s_add_u32 s10, s50, 0x15600000
	s_addc_u32 s11, s51, 0
	s_mul_i32 s3, s24, 0x210
	s_mul_hi_i32 s2, s24, 0x210
	s_add_u32 s3, s3, 0x200
	s_addc_u32 s2, s2, 0
	v_lshlrev_b32_e32 v11, 2, v18
	v_or_b32_e32 v12, s3, v11
	v_mov_b32_e32 v13, s2
	v_lshlrev_b64 v[12:13], 10, v[12:13]
	v_lshl_add_u64 v[12:13], s[10:11], 0, v[12:13]
	v_lshlrev_b32_e32 v132, 2, v19
	v_mov_b32_e32 v133, 0
	v_lshl_add_u64 v[12:13], v[12:13], 0, v[132:133]
	v_lshlrev_b32_e32 v132, 2, v1
	s_movk_i32 s2, 0xff
	v_lshl_add_u64 v[12:13], v[12:13], 0, v[132:133]
	v_cmp_lt_u32_e32 vcc, s2, v0
	s_and_saveexec_b64 s[2:3], vcc
	s_xor_b64 s[2:3], exec, s[2:3]
	s_cbranch_execnz .LBB0_886
	s_andn2_saveexec_b64 s[2:3], s[2:3]
	s_cbranch_execnz .LBB0_887

; __device__ __forceinline__ void ssm_scan(LAS float* L, int item, const float* lam_re, const float* lam_im, const float* log_dt, const float* S, f16* X) {
;     ...
;     const int seg = tid >> 6, n = tid & 63, pg = dir * NG + g;
;     const float dt = expf(log_dt[pg]), lr = lam_re[pg * NS + n], li = lam_im[pg * NS + n];
;     float tr, ti, sr, si;
;     { const float er = expf((float)TC * lr * dt); float sn, cs; sincosf((float)TC * (li * dt), &sn, &cs); tr = er * cs; ti = er * sn; }
;     { const float er = expf((float)(33 * TC) * lr * dt); float sn, cs; sincosf((float)(33 * TC) * (li * dt), &sn, &cs); sr = er * cs; si = er * sn; }
;     const float* Sg = S + (size_t)g * NCH * 256 + dir * 128 + n;
;     f16* Xg = X + (size_t)g * XGS + dir * 128 + n;
;     float vr[33], vi[33];
; #pragma unroll
;     for (int i = 0; i < 33; ++i) { const int p = seg * 33 + i;
;         const int row = p < 8 ? NLC + b * 8 + (dir == 0 ? p : 7 - p) : b * 256 + (dir == 0 ? p - 8 : 255 - (p - 8));
;         vr[i] = Sg[(size_t)row * 256]; vi[i] = Sg[(size_t)row * 256 + 64]; }
.LBB0_896:
	s_or_b64 exec, exec, s[2:3]
	v_readlane_b32 s56, v254, 18
	s_and_b32 s0, s24, 0x7f
	v_readlane_b32 s57, v254, 19
	v_readlane_b32 s58, v254, 20
	v_readlane_b32 s59, v254, 21
	v_readlane_b32 s60, v254, 22
	v_readlane_b32 s61, v254, 23
	s_lshl_b32 s1, s0, 2
	v_readlane_b32 s62, v254, 24
	v_readlane_b32 s63, v254, 25
	v_readlane_b32 s64, v254, 26
	v_readlane_b32 s65, v254, 27
	s_mov_b64 s[56:57], s[60:61]
	v_mov_b32_e32 v37, v0
	v_mov_b32_e32 v2, s1
	s_mov_b64 s[58:59], s[62:63]
	s_mov_b64 s[60:61], s[64:65]
	global_load_dword v151, v2, s[60:61]
	v_and_b32_e32 v33, 63, v37
	v_lshlrev_b32_e32 v2, 2, v33
	v_lshl_or_b32 v4, s0, 8, v2
	global_load_dword v153, v4, s[58:59]
	global_load_dword v45, v4, s[56:57]
	s_lshl_b32 s0, s84, 7
	s_or_b32 s0, s0, s24
	s_and_b32 s1, s24, 63
	s_ashr_i32 s5, s0, 7
	s_bfe_u32 s4, s24, 0x10006
	s_mul_i32 s0, s1, 0x84000
	s_add_u32 s0, s10, s0
	s_addc_u32 s3, s11, 0
	s_lshl_b32 s2, s4, 9
	s_add_u32 s2, s0, s2
	s_addc_u32 s3, s3, 0
	s_lshl_b32 s0, s5, 8
	v_ashrrev_i32_e32 v43, 6, v37
	v_mov_b32_e32 v3, 0
	s_cmp_eq_u32 s4, 0
	v_lshl_add_u64 v[2:3], s[2:3], 0, v[2:3]
	v_cmp_gt_i32_e64 s[2:3], 1, v43
	s_cselect_b64 vcc, -1, 0
	s_lshl_b32 s5, s5, 3
	v_mov_b32_e32 v9, 0x105
	v_lshl_add_u32 v31, v43, 5, v43
	s_addk_i32 s5, 0x200
	v_cndmask_b32_e64 v8, -6, 2, s[2:3]
	v_cndmask_b32_e64 v9, v9, 5, s[2:3]
	v_mov_b32_e32 v6, s0
	v_mov_b32_e32 v7, s5
	v_add_u32_e32 v8, v31, v8
	v_sub_u32_e32 v9, v9, v31
	v_cndmask_b32_e64 v18, v6, v7, s[2:3]
	v_cndmask_b32_e32 v8, v9, v8, vcc
	v_add_u32_e32 v8, v8, v18
	v_ashrrev_i32_e32 v9, 31, v8
	v_mov_b32_e32 v4, 0x107
	v_mov_b32_e32 v7, 0x106
	v_lshlrev_b64 v[8:9], 10, v[8:9]
	v_add_u32_e32 v55, -8, v31
	v_cndmask_b32_e64 v4, v4, 7, s[2:3]
	v_cndmask_b32_e64 v6, -7, 1, s[2:3]
	v_cndmask_b32_e64 v7, v7, 6, s[2:3]
	v_lshl_add_u64 v[10:11], v[2:3], 0, v[8:9]
	v_mov_b32_e32 v9, 0x104
	v_cndmask_b32_e64 v5, v55, v31, s[2:3]
	v_sub_u32_e32 v4, v4, v31
	v_add_u32_e32 v6, v31, v6
	v_sub_u32_e32 v7, v7, v31
	v_cndmask_b32_e64 v8, -5, 3, s[2:3]
	v_cndmask_b32_e64 v9, v9, 4, s[2:3]
	v_cndmask_b32_e32 v4, v4, v5, vcc
	v_cndmask_b32_e32 v6, v7, v6, vcc
	v_add_u32_e32 v8, v31, v8
	v_sub_u32_e32 v9, v9, v31
	v_add_u32_e32 v4, v4, v18
	v_add_u32_e32 v6, v6, v18
	v_cndmask_b32_e32 v8, v9, v8, vcc
	v_ashrrev_i32_e32 v5, 31, v4
	v_ashrrev_i32_e32 v7, 31, v6
	v_add_u32_e32 v8, v8, v18
	v_lshlrev_b64 v[4:5], 10, v[4:5]
	v_lshlrev_b64 v[6:7], 10, v[6:7]
	v_ashrrev_i32_e32 v9, 31, v8
	v_lshl_add_u64 v[4:5], v[2:3], 0, v[4:5]
	v_lshl_add_u64 v[6:7], v[2:3], 0, v[6:7]
	v_lshlrev_b64 v[8:9], 10, v[8:9]
	v_lshl_add_u64 v[12:13], v[2:3], 0, v[8:9]
	global_load_dword v8, v[4:5], off
	global_load_dword v9, v[4:5], off offset:256
	global_load_dword v41, v[6:7], off
	global_load_dword v40, v[6:7], off offset:256
	s_nop 0
	global_load_dword v6, v[10:11], off
	global_load_dword v7, v[10:11], off offset:256
	global_load_dword v38, v[12:13], off
	global_load_dword v36, v[12:13], off offset:256
	v_bfrev_b32_e32 v11, 4.0
	v_cndmask_b32_e64 v10, -3, 5, s[2:3]
	v_cndmask_b32_e64 v11, v11, 2, s[2:3]
	v_add_u32_e32 v10, v31, v10
	v_sub_u32_e32 v11, v11, v31
	v_cndmask_b32_e32 v10, v11, v10, vcc
	v_add_u32_e32 v10, v10, v18
	v_ashrrev_i32_e32 v11, 31, v10
	v_lshlrev_b64 v[10:11], 10, v[10:11]
	v_lshl_add_u64 v[14:15], v[2:3], 0, v[10:11]
	v_mov_b32_e32 v11, 0x101
	v_cndmask_b32_e64 v10, -2, 6, s[2:3]
	v_cndmask_b32_e64 v11, v11, 1, s[2:3]
	v_add_u32_e32 v10, v31, v10
	v_sub_u32_e32 v11, v11, v31
	v_cndmask_b32_e32 v10, v11, v10, vcc
	v_add_u32_e32 v10, v10, v18
	v_ashrrev_i32_e32 v11, 31, v10
	v_bfrev_b32_e32 v5, -4.0
	v_lshlrev_b64 v[10:11], 10, v[10:11]
	v_cndmask_b32_e64 v4, -4, 4, s[2:3]
	v_cndmask_b32_e64 v5, v5, 3, s[2:3]
	v_lshl_add_u64 v[16:17], v[2:3], 0, v[10:11]
	v_mov_b32_e32 v11, 0x100
	v_add_u32_e32 v4, v31, v4
	v_sub_u32_e32 v5, v5, v31
	v_cndmask_b32_e64 v10, -1, 7, s[2:3]
	v_cndmask_b32_e64 v11, v11, 0, s[2:3]
	v_cndmask_b32_e32 v4, v5, v4, vcc
	v_add_u32_e32 v10, v31, v10
	v_sub_u32_e32 v11, v11, v31
	v_add_u32_e32 v4, v4, v18
	v_cndmask_b32_e32 v10, v11, v10, vcc
	v_ashrrev_i32_e32 v5, 31, v4
	v_add_u32_e32 v10, v10, v18
	v_lshlrev_b64 v[4:5], 10, v[4:5]
	v_ashrrev_i32_e32 v11, 31, v10
	v_lshl_add_u64 v[4:5], v[2:3], 0, v[4:5]
	v_lshlrev_b64 v[10:11], 10, v[10:11]
	v_lshl_add_u64 v[18:19], v[2:3], 0, v[10:11]
	global_load_dword v12, v[4:5], off
	global_load_dword v13, v[4:5], off offset:256
	global_load_dword v49, v[14:15], off
	global_load_dword v48, v[14:15], off offset:256
	global_load_dword v10, v[16:17], off
	global_load_dword v11, v[16:17], off offset:256
	global_load_dword v44, v[18:19], off
	global_load_dword v42, v[18:19], off offset:256
	v_cmp_lt_i32_e64 s[2:3], -1, v43
	s_and_saveexec_b64 s[6:7], s[2:3]
	s_xor_b64 s[2:3], exec, s[6:7]
	v_sub_u32_e32 v4, 0xff, v31
	v_cndmask_b32_e32 v4, v4, v31, vcc
	v_add_u32_e32 v4, s0, v4
	s_or_saveexec_b64 s[2:3], s[2:3]
	v_mov_b32_e32 v85, 1
	v_mov_b32_e32 v86, 0xfe
	v_mov_b32_e32 v16, 2
	v_bfrev_b32_e32 v17, -0.5
	v_mov_b32_e32 v14, 3
	v_bfrev_b32_e32 v15, 0.5
	v_mov_b32_e32 v83, 4
	v_mov_b32_e32 v84, 0xfb
	v_mov_b32_e32 v81, 5
	v_mov_b32_e32 v82, 0xfa
	v_mov_b32_e32 v20, 6
	v_mov_b32_e32 v21, 0xf9
	v_mov_b32_e32 v18, 7
	v_mov_b32_e32 v19, 0xf8
	v_mov_b32_e32 v79, 8
	v_mov_b32_e32 v80, 0xf7
	v_mov_b32_e32 v77, 9
	v_mov_b32_e32 v78, 0xf6
	v_mov_b32_e32 v24, 10
	v_mov_b32_e32 v25, 0xf5
	v_mov_b32_e32 v22, 11
	v_mov_b32_e32 v23, 0xf4
	v_mov_b32_e32 v75, 12
	v_mov_b32_e32 v76, 0xf3
	v_mov_b32_e32 v73, 13
	v_mov_b32_e32 v74, 0xf2
	v_mov_b32_e32 v28, 14
	v_mov_b32_e32 v29, 0xf1
	v_mov_b32_e32 v26, 15
	v_mov_b32_e32 v27, 0xf0
	v_mov_b32_e32 v71, 16
	v_mov_b32_e32 v72, 0xef
	v_mov_b32_e32 v69, 17
	v_mov_b32_e32 v70, 0xee
	v_mov_b32_e32 v50, 18
	v_mov_b32_e32 v51, 0xed
	v_mov_b32_e32 v46, 19
	v_mov_b32_e32 v47, 0xec
	v_mov_b32_e32 v66, 20
	v_mov_b32_e32 v68, 0xeb
	v_mov_b32_e32 v63, 21
	v_mov_b32_e32 v64, 0xea
	v_mov_b32_e32 v60, 22
	v_mov_b32_e32 v62, 0xe9
	v_mov_b32_e32 v57, 23
	v_mov_b32_e32 v58, 0xe8
	v_mov_b32_e32 v52, 24
	v_mov_b32_e32 v54, 0xe7
	v_mov_b32_e32 v56, s0
	v_add_u32_e32 v39, 8, v31
	s_xor_b64 exec, exec, s[2:3]
	s_cbranch_execz .LBB0_908
; __device__ __forceinline__ void ssm_scan(LAS float* L, int item, const float* lam_re, const float* lam_im, const float* log_dt, const float* S, f16* X) {
;     ...
;     for (int i = 0; i < 33; ++i) { const int p = seg * 33 + i;
;         const int row = p < 8 ? NLC + b * 8 + (dir == 0 ? p : 7 - p) : b * 256 + (dir == 0 ? p - 8 : 255 - (p - 8));
;         vr[i] = Sg[(size_t)row * 256]; vi[i] = Sg[(size_t)row * 256 + 64]; }
	v_not_b32_e32 v4, v31
	v_cndmask_b32_e32 v4, v4, v39, vcc
	v_add_u32_e32 v4, s5, v4
	v_mov_b32_e32 v85, 9
	v_mov_b32_e32 v86, -2
	v_mov_b32_e32 v16, 10
	v_mov_b32_e32 v17, -3
	v_mov_b32_e32 v14, 11
	v_mov_b32_e32 v15, -4
	v_mov_b32_e32 v83, 12
	v_mov_b32_e32 v84, -5
	v_mov_b32_e32 v81, 13
	v_mov_b32_e32 v82, -6
	v_mov_b32_e32 v20, 14
	v_mov_b32_e32 v21, -7
	v_mov_b32_e32 v18, 15
	v_mov_b32_e32 v19, -8
	v_mov_b32_e32 v79, 16
	v_mov_b32_e32 v80, -9
	v_mov_b32_e32 v77, 17
	v_mov_b32_e32 v78, -10
	v_mov_b32_e32 v24, 18
	v_mov_b32_e32 v25, -11
	v_mov_b32_e32 v22, 19
	v_mov_b32_e32 v23, -12
	v_mov_b32_e32 v75, 20
	v_mov_b32_e32 v76, -13
	v_mov_b32_e32 v73, 21
	v_mov_b32_e32 v74, -14
	v_mov_b32_e32 v28, 22
	v_mov_b32_e32 v29, -15
	v_mov_b32_e32 v26, 23
	v_mov_b32_e32 v27, -16
	v_mov_b32_e32 v71, 24
	v_not_b32_e32 v72, 16
	v_mov_b32_e32 v69, 25
	v_not_b32_e32 v70, 17
	v_mov_b32_e32 v50, 26
	v_not_b32_e32 v51, 18
	v_mov_b32_e32 v46, 27
	v_not_b32_e32 v47, 19
	v_mov_b32_e32 v66, 28
	v_not_b32_e32 v68, 20
	v_mov_b32_e32 v63, 29
	v_not_b32_e32 v64, 21
	v_mov_b32_e32 v60, 30
	v_not_b32_e32 v62, 22
	v_mov_b32_e32 v57, 31
	v_not_b32_e32 v58, 23
	v_mov_b32_e32 v52, 32
	v_not_b32_e32 v54, 24
	v_mov_b32_e32 v56, s5
.LBB0_908:
	s_or_b64 exec, exec, s[2:3]
	v_add_u32_e32 v85, v31, v85
	v_sub_u32_e32 v86, v86, v31
	v_add_u32_e32 v16, v31, v16
	v_sub_u32_e32 v17, v17, v31
	v_add_u32_e32 v14, v31, v14
	v_sub_u32_e32 v15, v15, v31
	v_cndmask_b32_e32 v85, v86, v85, vcc
	v_cndmask_b32_e32 v16, v17, v16, vcc
	v_cndmask_b32_e32 v14, v15, v14, vcc
	v_ashrrev_i32_e32 v5, 31, v4
	v_add_u32_e32 v86, v85, v56
	v_add_u32_e32 v16, v16, v56
	v_add_u32_e32 v14, v14, v56
	v_lshlrev_b64 v[4:5], 10, v[4:5]
	v_ashrrev_i32_e32 v87, 31, v86
	v_ashrrev_i32_e32 v17, 31, v16
	v_ashrrev_i32_e32 v15, 31, v14
	v_lshl_add_u64 v[4:5], v[2:3], 0, v[4:5]
	v_lshlrev_b64 v[86:87], 10, v[86:87]
	v_lshlrev_b64 v[16:17], 10, v[16:17]
	v_lshlrev_b64 v[14:15], 10, v[14:15]
	v_lshl_add_u64 v[86:87], v[2:3], 0, v[86:87]
	v_lshl_add_u64 v[88:89], v[2:3], 0, v[16:17]
	v_lshl_add_u64 v[90:91], v[2:3], 0, v[14:15]
	global_load_dword v16, v[4:5], off
	global_load_dword v17, v[4:5], off offset:256
	global_load_dword v95, v[86:87], off
	global_load_dword v97, v[86:87], off offset:256
	global_load_dword v14, v[88:89], off
	global_load_dword v15, v[88:89], off offset:256
	global_load_dword v101, v[90:91], off
	global_load_dword v103, v[90:91], off offset:256
	v_add_u32_e32 v4, v31, v83
	v_sub_u32_e32 v5, v84, v31
	v_cndmask_b32_e32 v4, v5, v4, vcc
	v_add_u32_e32 v81, v31, v81
	v_sub_u32_e32 v82, v82, v31
	v_add_u32_e32 v20, v31, v20
	v_sub_u32_e32 v21, v21, v31
	v_add_u32_e32 v18, v31, v18
	v_sub_u32_e32 v19, v19, v31
	v_add_u32_e32 v4, v4, v56
	v_cndmask_b32_e32 v81, v82, v81, vcc
	v_cndmask_b32_e32 v20, v21, v20, vcc
	v_cndmask_b32_e32 v18, v19, v18, vcc
	v_ashrrev_i32_e32 v5, 31, v4
	v_add_u32_e32 v82, v81, v56
	v_add_u32_e32 v20, v20, v56
	v_add_u32_e32 v18, v18, v56
	v_lshlrev_b64 v[4:5], 10, v[4:5]
	v_ashrrev_i32_e32 v83, 31, v82
	v_ashrrev_i32_e32 v21, 31, v20
	v_ashrrev_i32_e32 v19, 31, v18
	v_lshl_add_u64 v[4:5], v[2:3], 0, v[4:5]
	v_lshlrev_b64 v[82:83], 10, v[82:83]
	v_lshlrev_b64 v[20:21], 10, v[20:21]
	v_lshlrev_b64 v[18:19], 10, v[18:19]
	v_lshl_add_u64 v[82:83], v[2:3], 0, v[82:83]
	v_lshl_add_u64 v[84:85], v[2:3], 0, v[20:21]
	v_lshl_add_u64 v[86:87], v[2:3], 0, v[18:19]
	global_load_dword v20, v[4:5], off
	global_load_dword v21, v[4:5], off offset:256
	global_load_dword v91, v[82:83], off
	global_load_dword v114, v[82:83], off offset:256
	global_load_dword v18, v[84:85], off
	global_load_dword v19, v[84:85], off offset:256
	global_load_dword v115, v[86:87], off
	global_load_dword v116, v[86:87], off offset:256
	v_add_u32_e32 v4, v31, v79
	v_sub_u32_e32 v5, v80, v31
	v_cndmask_b32_e32 v4, v5, v4, vcc
	v_add_u32_e32 v77, v31, v77
	v_sub_u32_e32 v78, v78, v31
	v_add_u32_e32 v24, v31, v24
	v_sub_u32_e32 v25, v25, v31
	v_add_u32_e32 v22, v31, v22
	v_sub_u32_e32 v23, v23, v31
	v_add_u32_e32 v4, v4, v56
	v_cndmask_b32_e32 v77, v78, v77, vcc
	v_cndmask_b32_e32 v24, v25, v24, vcc
	v_cndmask_b32_e32 v22, v23, v22, vcc
	v_ashrrev_i32_e32 v5, 31, v4
	v_add_u32_e32 v78, v77, v56
	v_add_u32_e32 v24, v24, v56
	v_add_u32_e32 v22, v22, v56
	v_lshlrev_b64 v[4:5], 10, v[4:5]
	v_ashrrev_i32_e32 v79, 31, v78
	v_ashrrev_i32_e32 v25, 31, v24
	v_ashrrev_i32_e32 v23, 31, v22
	v_lshl_add_u64 v[4:5], v[2:3], 0, v[4:5]
	v_lshlrev_b64 v[78:79], 10, v[78:79]
	v_lshlrev_b64 v[24:25], 10, v[24:25]
	v_lshlrev_b64 v[22:23], 10, v[22:23]
	v_lshl_add_u64 v[78:79], v[2:3], 0, v[78:79]
	v_lshl_add_u64 v[80:81], v[2:3], 0, v[24:25]
	v_lshl_add_u64 v[82:83], v[2:3], 0, v[22:23]
	global_load_dword v24, v[4:5], off
	global_load_dword v25, v[4:5], off offset:256
	global_load_dword v117, v[78:79], off
	global_load_dword v118, v[78:79], off offset:256
	global_load_dword v22, v[80:81], off
	global_load_dword v23, v[80:81], off offset:256
	global_load_dword v119, v[82:83], off
	global_load_dword v120, v[82:83], off offset:256
	v_add_u32_e32 v4, v31, v75
	v_sub_u32_e32 v5, v76, v31
	v_cndmask_b32_e32 v4, v5, v4, vcc
	v_add_u32_e32 v73, v31, v73
	v_sub_u32_e32 v74, v74, v31
	v_add_u32_e32 v28, v31, v28
	v_sub_u32_e32 v29, v29, v31
	v_add_u32_e32 v26, v31, v26
	v_sub_u32_e32 v27, v27, v31
	v_add_u32_e32 v4, v4, v56
	v_cndmask_b32_e32 v73, v74, v73, vcc
	v_cndmask_b32_e32 v28, v29, v28, vcc
	v_cndmask_b32_e32 v26, v27, v26, vcc
	v_ashrrev_i32_e32 v5, 31, v4
	v_add_u32_e32 v74, v73, v56
	v_add_u32_e32 v28, v28, v56
	v_add_u32_e32 v26, v26, v56
	v_lshlrev_b64 v[4:5], 10, v[4:5]
	v_ashrrev_i32_e32 v75, 31, v74
	v_ashrrev_i32_e32 v29, 31, v28
; __device__ __forceinline__ void ssm_scan(LAS float* L, int item, const float* lam_re, const float* lam_im, const float* log_dt, const float* S, f16* X) {
;     ...
;     const float dt = expf(log_dt[pg]), lr = lam_re[pg * NS + n], li = lam_im[pg * NS + n];
;     float tr, ti, sr, si;
;     { const float er = expf((float)TC * lr * dt); float sn, cs; sincosf((float)TC * (li * dt), &sn, &cs); tr = er * cs; ti = er * sn; }
;     { const float er = expf((float)(33 * TC) * lr * dt); float sn, cs; sincosf((float)(33 * TC) * (li * dt), &sn, &cs); sr = er * cs; si = er * sn; }
;     ...
;     for (int i = 0; i < 33; ++i) { const int p = seg * 33 + i;
;         const int row = p < 8 ? NLC + b * 8 + (dir == 0 ? p : 7 - p) : b * 256 + (dir == 0 ? p - 8 : 255 - (p - 8));
;         vr[i] = Sg[(size_t)row * 256]; vi[i] = Sg[(size_t)row * 256 + 64]; }
	v_ashrrev_i32_e32 v27, 31, v26
	v_lshl_add_u64 v[4:5], v[2:3], 0, v[4:5]
	v_lshlrev_b64 v[74:75], 10, v[74:75]
	v_lshlrev_b64 v[28:29], 10, v[28:29]
	v_lshlrev_b64 v[26:27], 10, v[26:27]
	v_lshl_add_u64 v[74:75], v[2:3], 0, v[74:75]
	v_lshl_add_u64 v[76:77], v[2:3], 0, v[28:29]
	v_lshl_add_u64 v[78:79], v[2:3], 0, v[26:27]
	global_load_dword v28, v[4:5], off
	global_load_dword v29, v[4:5], off offset:256
	global_load_dword v121, v[74:75], off
	global_load_dword v122, v[74:75], off offset:256
	global_load_dword v26, v[76:77], off
	global_load_dword v27, v[76:77], off offset:256
	global_load_dword v123, v[78:79], off
	global_load_dword v124, v[78:79], off offset:256
	v_add_u32_e32 v4, v31, v71
	v_sub_u32_e32 v5, v72, v31
	v_cndmask_b32_e32 v4, v5, v4, vcc
	v_add_u32_e32 v69, v31, v69
	v_sub_u32_e32 v70, v70, v31
	v_add_u32_e32 v50, v31, v50
	v_sub_u32_e32 v51, v51, v31
	v_add_u32_e32 v46, v31, v46
	v_sub_u32_e32 v47, v47, v31
	v_add_u32_e32 v4, v4, v56
	v_cndmask_b32_e32 v69, v70, v69, vcc
	v_cndmask_b32_e32 v50, v51, v50, vcc
	v_cndmask_b32_e32 v46, v47, v46, vcc
	v_ashrrev_i32_e32 v5, 31, v4
	v_add_u32_e32 v70, v69, v56
	v_add_u32_e32 v50, v50, v56
	v_add_u32_e32 v46, v46, v56
	v_lshlrev_b64 v[4:5], 10, v[4:5]
	v_ashrrev_i32_e32 v71, 31, v70
	v_ashrrev_i32_e32 v51, 31, v50
	v_ashrrev_i32_e32 v47, 31, v46
	v_lshl_add_u64 v[4:5], v[2:3], 0, v[4:5]
	v_lshlrev_b64 v[70:71], 10, v[70:71]
	v_lshlrev_b64 v[50:51], 10, v[50:51]
	v_lshlrev_b64 v[46:47], 10, v[46:47]
	v_lshl_add_u64 v[70:71], v[2:3], 0, v[70:71]
	v_lshl_add_u64 v[72:73], v[2:3], 0, v[50:51]
	v_lshl_add_u64 v[74:75], v[2:3], 0, v[46:47]
	global_load_dword v50, v[4:5], off
	global_load_dword v51, v[4:5], off offset:256
	global_load_dword v125, v[70:71], off
	global_load_dword v126, v[70:71], off offset:256
	global_load_dword v46, v[72:73], off
	global_load_dword v47, v[72:73], off offset:256
	global_load_dword v127, v[74:75], off
	global_load_dword v128, v[74:75], off offset:256
	v_add_u32_e32 v4, v31, v66
	v_sub_u32_e32 v5, v68, v31
	v_cndmask_b32_e32 v4, v5, v4, vcc
	v_add_u32_e32 v63, v31, v63
	v_sub_u32_e32 v64, v64, v31
	v_add_u32_e32 v60, v31, v60
	v_sub_u32_e32 v62, v62, v31
	v_add_u32_e32 v57, v31, v57
	v_sub_u32_e32 v58, v58, v31
	v_add_u32_e32 v4, v4, v56
	v_cndmask_b32_e32 v63, v64, v63, vcc
	v_cndmask_b32_e32 v60, v62, v60, vcc
	v_cndmask_b32_e32 v57, v58, v57, vcc
	v_ashrrev_i32_e32 v5, 31, v4
	v_add_u32_e32 v68, v63, v56
	v_add_u32_e32 v62, v60, v56
	v_add_u32_e32 v70, v57, v56
	v_lshlrev_b64 v[4:5], 10, v[4:5]
	v_ashrrev_i32_e32 v69, 31, v68
	v_ashrrev_i32_e32 v63, 31, v62
	v_ashrrev_i32_e32 v71, 31, v70
	v_lshl_add_u64 v[4:5], v[2:3], 0, v[4:5]
	v_lshlrev_b64 v[68:69], 10, v[68:69]
	v_lshlrev_b64 v[62:63], 10, v[62:63]
	v_lshlrev_b64 v[70:71], 10, v[70:71]
	v_lshl_add_u64 v[68:69], v[2:3], 0, v[68:69]
	v_lshl_add_u64 v[62:63], v[2:3], 0, v[62:63]
	v_lshl_add_u64 v[70:71], v[2:3], 0, v[70:71]
	global_load_dword v112, v[4:5], off
	global_load_dword v113, v[4:5], off offset:256
	global_load_dword v129, v[68:69], off
	global_load_dword v131, v[68:69], off offset:256
	global_load_dword v110, v[62:63], off
	global_load_dword v111, v[62:63], off offset:256
	global_load_dword v134, v[70:71], off
	global_load_dword v135, v[70:71], off offset:256
	v_add_u32_e32 v4, v31, v52
	v_sub_u32_e32 v5, v54, v31
	v_cndmask_b32_e32 v4, v5, v4, vcc
	v_add_u32_e32 v4, v4, v56
	v_ashrrev_i32_e32 v5, 31, v4
	v_lshlrev_b64 v[4:5], 10, v[4:5]
	v_lshl_add_u64 v[2:3], v[2:3], 0, v[4:5]
	global_load_dword v108, v[2:3], off
	global_load_dword v109, v[2:3], off offset:256
	s_mov_b64 s[96:97], vcc
	s_mov_b32 s18, 0x3fb8aa3b
	s_mov_b32 s19, 0xc2ce8ed0
	s_brev_b32 s2, 18
	v_readlane_b32 s66, v254, 28
	v_readlane_b32 s67, v254, 29
	v_readlane_b32 s68, v254, 30
	v_readlane_b32 s69, v254, 31
	v_readlane_b32 s70, v254, 32
	v_readlane_b32 s71, v254, 33
	s_waitcnt vmcnt(63)
	v_mul_f32_e32 v152, 0x3fb8aa3b, v151
	v_fma_f32 v154, v151, s18, -v152
	v_rndne_f32_e32 v155, v152
	v_fmamk_f32 v154, v151, 0x32a5705f, v154
	v_sub_f32_e32 v152, v152, v155
	v_add_f32_e32 v152, v152, v154
	v_cvt_i32_f32_e32 v155, v155
	v_exp_f32_e32 v152, v152
	s_mov_b32 s18, 0x42b17218
	v_cmp_ngt_f32_e32 vcc, s19, v151
	v_mov_b32_e32 v154, 0x7f800000
	v_ldexp_f32 v152, v152, v155
	v_cndmask_b32_e32 v152, 0, v152, vcc
	v_cmp_nlt_f32_e32 vcc, s18, v151
	s_nop 1
	v_cndmask_b32_e32 v53, v154, v152, vcc
	s_waitcnt vmcnt(63)
	v_mul_f32_e32 v151, v53, v153
	v_mul_f32_e32 v30, 0x42000000, v151
	v_and_b32_e32 v32, 0x7fffffff, v30
	v_cmp_nlt_f32_e64 s[18:19], |v30|, s2
	s_and_saveexec_b64 s[2:3], s[18:19]
	s_xor_b64 s[12:13], exec, s[2:3]
	s_cbranch_execz .LBB0_898
; __device__ __forceinline__ void ssm_scan(LAS float* L, int item, const float* lam_re, const float* lam_im, const float* log_dt, const float* S, f16* X) {
;     ...
;     { const float er = expf((float)TC * lr * dt); float sn, cs; sincosf((float)TC * (li * dt), &sn, &cs); tr = er * cs; ti = er * sn; }
;     { const float er = expf((float)(33 * TC) * lr * dt); float sn, cs; sincosf((float)(33 * TC) * (li * dt), &sn, &cs); sr = er * cs; si = er * sn; }
	v_lshrrev_b32_e32 v152, 23, v32
	v_add_u32_e32 v152, 0xffffff88, v152
	v_not_b32_e32 v153, 63
	v_cmp_lt_u32_e32 vcc, 63, v152
	s_mov_b32 s18, 0xfe5163ab
	v_mov_b32_e32 v155, 0
	v_cndmask_b32_e32 v153, 0, v153, vcc
	v_add_u32_e32 v152, v153, v152
	v_not_b32_e32 v153, 31
	v_cmp_lt_u32_e64 s[2:3], 31, v152
	s_nop 1
	v_cndmask_b32_e64 v154, 0, v153, s[2:3]
	v_add_u32_e32 v152, v154, v152
	v_cmp_lt_u32_e64 s[20:21], 31, v152
	s_nop 1
	v_cndmask_b32_e64 v153, 0, v153, s[20:21]
	v_add_u32_e32 v166, v153, v152
	v_and_b32_e32 v152, 0x7fffff, v32
	v_or_b32_e32 v167, 0x800000, v152
	v_mad_u64_u32 v[152:153], s[18:19], v167, s18, 0
	v_mov_b32_e32 v154, v153
	s_mov_b32 s18, 0x3c439041
	v_mad_u64_u32 v[156:157], s[18:19], v167, s18, v[154:155]
	v_mov_b32_e32 v154, v157
	s_mov_b32 s18, 0xdb629599
	v_mad_u64_u32 v[158:159], s[18:19], v167, s18, v[154:155]
	v_mov_b32_e32 v154, v159
	s_mov_b32 s18, 0xf534ddc0
	v_mad_u64_u32 v[160:161], s[18:19], v167, s18, v[154:155]
	v_mov_b32_e32 v154, v161
	s_mov_b32 s18, 0xfc2757d1
	v_mad_u64_u32 v[162:163], s[18:19], v167, s18, v[154:155]
	v_mov_b32_e32 v154, v163
	s_mov_b32 s18, 0x4e441529
	v_mad_u64_u32 v[164:165], s[18:19], v167, s18, v[154:155]
	v_mov_b32_e32 v154, v165
	s_mov_b32 s18, 0xa2f9836e
	v_mad_u64_u32 v[154:155], s[18:19], v167, s18, v[154:155]
	v_cndmask_b32_e32 v153, v164, v160, vcc
	v_cndmask_b32_e32 v154, v154, v162, vcc
	v_cndmask_b32_e32 v155, v155, v164, vcc
	v_cndmask_b32_e64 v157, v154, v153, s[2:3]
	v_cndmask_b32_e64 v154, v155, v154, s[2:3]
	v_cndmask_b32_e32 v155, v162, v158, vcc
	v_cndmask_b32_e64 v153, v153, v155, s[2:3]
	v_cndmask_b32_e32 v156, v160, v156, vcc
	v_cndmask_b32_e64 v154, v154, v157, s[20:21]
	v_cndmask_b32_e64 v157, v157, v153, s[20:21]
	v_sub_u32_e32 v159, 32, v166
	v_cndmask_b32_e64 v155, v155, v156, s[2:3]
	v_alignbit_b32 v161, v154, v157, v159
	v_cmp_eq_u32_e64 s[6:7], 0, v166
	v_cndmask_b32_e64 v153, v153, v155, s[20:21]
	v_alignbit_b32 v160, v157, v153, v159
	v_cndmask_b32_e64 v154, v161, v154, s[6:7]
	v_cndmask_b32_e32 v152, v158, v152, vcc
	v_cndmask_b32_e64 v157, v160, v157, s[6:7]
	v_bfe_u32 v162, v154, 29, 1
	v_cndmask_b32_e64 v152, v156, v152, s[2:3]
	v_alignbit_b32 v160, v154, v157, 30
	v_sub_u32_e32 v163, 0, v162
	v_cndmask_b32_e64 v152, v155, v152, s[20:21]
	v_xor_b32_e32 v160, v160, v163
	v_alignbit_b32 v155, v153, v152, v159
	v_cndmask_b32_e64 v153, v155, v153, s[6:7]
	v_ffbh_u32_e32 v156, v160
	v_alignbit_b32 v155, v157, v153, 30
	v_min_u32_e32 v156, 32, v156
	v_alignbit_b32 v152, v153, v152, 30
	v_xor_b32_e32 v155, v155, v163
	v_sub_u32_e32 v157, 31, v156
	v_xor_b32_e32 v152, v152, v163
	v_alignbit_b32 v158, v160, v155, v157
	v_alignbit_b32 v152, v155, v152, v157
	v_alignbit_b32 v153, v158, v152, 9
	v_ffbh_u32_e32 v155, v153
	v_min_u32_e32 v155, 32, v155
	v_lshrrev_b32_e32 v161, 29, v154
	v_not_b32_e32 v157, v155
	v_alignbit_b32 v152, v153, v152, v157
	v_lshlrev_b32_e32 v153, 31, v161
	v_or_b32_e32 v157, 0x33000000, v153
	v_add_lshl_u32 v155, v155, v156, 23
	v_lshrrev_b32_e32 v152, 9, v152
	v_sub_u32_e32 v155, v157, v155
	v_or_b32_e32 v153, 0.5, v153
	v_lshlrev_b32_e32 v156, 23, v156
	v_or_b32_e32 v152, v155, v152
	v_lshrrev_b32_e32 v155, 9, v158
	v_sub_u32_e32 v153, v153, v156
	v_or_b32_e32 v153, v155, v153
	s_mov_b32 s18, 0x3fc90fda
	v_mul_f32_e32 v155, 0x3fc90fda, v153
	v_fma_f32 v156, v153, s18, -v155
	v_fmamk_f32 v153, v153, 0x33a22168, v156
	v_fmac_f32_e32 v153, 0x3fc90fda, v152
	v_lshrrev_b32_e32 v152, 30, v154
	v_add_f32_e32 v34, v155, v153
	v_add_u32_e32 v35, v162, v152
.LBB0_898:
	s_andn2_saveexec_b64 s[2:3], s[12:13]
	s_cbranch_execz .LBB0_900
	s_mov_b32 s18, 0x3f22f983
	v_mul_f32_e64 v152, |v30|, s18
	v_rndne_f32_e32 v152, v152
	s_mov_b32 s18, 0xbfc90fda
	v_cvt_i32_f32_e32 v35, v152
	v_fma_f32 v153, v152, s18, |v30|
	v_fmamk_f32 v153, v152, 0xb3a22168, v153
	v_fmamk_f32 v34, v152, 0xa7c234c4, v153
.LBB0_900:
	s_or_b64 exec, exec, s[2:3]
	v_mul_f32_e32 v59, 0x44840000, v151
	s_brev_b32 s18, 18
	v_and_b32_e32 v61, 0x7fffffff, v59
	v_cmp_nlt_f32_e64 s[18:19], |v59|, s18
	s_and_saveexec_b64 s[2:3], s[18:19]
	s_xor_b64 s[12:13], exec, s[2:3]
	s_cbranch_execz .LBB0_902
	v_lshrrev_b32_e32 v151, 23, v61
	v_add_u32_e32 v151, 0xffffff88, v151
	v_not_b32_e32 v152, 63
	v_cmp_lt_u32_e32 vcc, 63, v151
	s_mov_b32 s18, 0xfe5163ab
	v_mov_b32_e32 v155, 0
	v_cndmask_b32_e32 v152, 0, v152, vcc
	v_add_u32_e32 v151, v152, v151
	v_not_b32_e32 v152, 31
	v_cmp_lt_u32_e64 s[2:3], 31, v151
	s_nop 1
	v_cndmask_b32_e64 v153, 0, v152, s[2:3]
	v_add_u32_e32 v151, v153, v151
	v_cmp_lt_u32_e64 s[20:21], 31, v151
	s_nop 1
	v_cndmask_b32_e64 v152, 0, v152, s[20:21]
	v_add_u32_e32 v151, v152, v151
	v_and_b32_e32 v152, 0x7fffff, v61
	v_or_b32_e32 v166, 0x800000, v152
	v_mad_u64_u32 v[152:153], s[18:19], v166, s18, 0
	v_mov_b32_e32 v154, v153
	s_mov_b32 s18, 0x3c439041
	v_mad_u64_u32 v[156:157], s[18:19], v166, s18, v[154:155]
	v_mov_b32_e32 v154, v157
	s_mov_b32 s18, 0xdb629599
	v_mad_u64_u32 v[158:159], s[18:19], v166, s18, v[154:155]
	v_mov_b32_e32 v154, v159
	s_mov_b32 s18, 0xf534ddc0
	v_mad_u64_u32 v[160:161], s[18:19], v166, s18, v[154:155]
	v_mov_b32_e32 v154, v161
	s_mov_b32 s18, 0xfc2757d1
	v_mad_u64_u32 v[162:163], s[18:19], v166, s18, v[154:155]
	v_mov_b32_e32 v154, v163
	s_mov_b32 s18, 0x4e441529
	v_mad_u64_u32 v[164:165], s[18:19], v166, s18, v[154:155]
	v_mov_b32_e32 v154, v165
	s_mov_b32 s18, 0xa2f9836e
	v_mad_u64_u32 v[154:155], s[18:19], v166, s18, v[154:155]
	v_cndmask_b32_e32 v153, v164, v160, vcc
	v_cndmask_b32_e32 v154, v154, v162, vcc
	v_cndmask_b32_e32 v155, v155, v164, vcc
	v_cndmask_b32_e64 v157, v154, v153, s[2:3]
	v_cndmask_b32_e64 v154, v155, v154, s[2:3]
; __device__ __forceinline__ void ssm_scan(LAS float* L, int item, const float* lam_re, const float* lam_im, const float* log_dt, const float* S, f16* X) {
;     ...
;     { const float er = expf((float)TC * lr * dt); float sn, cs; sincosf((float)TC * (li * dt), &sn, &cs); tr = er * cs; ti = er * sn; }
;     { const float er = expf((float)(33 * TC) * lr * dt); float sn, cs; sincosf((float)(33 * TC) * (li * dt), &sn, &cs); sr = er * cs; si = er * sn; }
;     const float* Sg = S + (size_t)g * NCH * 256 + dir * 128 + n;
;     f16* Xg = X + (size_t)g * XGS + dir * 128 + n;
;     float vr[33], vi[33];
; #pragma unroll
;     for (int i = 0; i < 33; ++i) { const int p = seg * 33 + i;
;         const int row = p < 8 ? NLC + b * 8 + (dir == 0 ? p : 7 - p) : b * 256 + (dir == 0 ? p - 8 : 255 - (p - 8));
;         vr[i] = Sg[(size_t)row * 256]; vi[i] = Sg[(size_t)row * 256 + 64]; }
;     __builtin_amdgcn_sched_barrier(0);
;     float hr = 0.f, hi = 0.f;
; #pragma unroll
;     for (int i = 0; i < 33; ++i) { const float s_r = vr[i], s_i = vi[i]; vr[i] = hr; vi[i] = hi; const float nr = tr * hr - ti * hi + s_r, ni = tr * hi + ti * hr + s_i; hr = nr; hi = ni; }
	v_cndmask_b32_e32 v155, v162, v158, vcc
	v_cndmask_b32_e64 v153, v153, v155, s[2:3]
	v_cndmask_b32_e64 v154, v154, v157, s[20:21]
	v_cndmask_b32_e64 v157, v157, v153, s[20:21]
	v_sub_u32_e32 v159, 32, v151
	v_alignbit_b32 v161, v154, v157, v159
	v_cmp_eq_u32_e64 s[6:7], 0, v151
	v_cndmask_b32_e32 v152, v158, v152, vcc
	s_mov_b32 s18, 0x3fc90fda
	v_cndmask_b32_e64 v151, v161, v154, s[6:7]
	v_cndmask_b32_e32 v154, v160, v156, vcc
	v_cndmask_b32_e64 v155, v155, v154, s[2:3]
	v_cndmask_b32_e64 v153, v153, v155, s[20:21]
	v_alignbit_b32 v156, v157, v153, v159
	v_cndmask_b32_e64 v156, v156, v157, s[6:7]
	v_bfe_u32 v161, v151, 29, 1
	v_cndmask_b32_e64 v152, v154, v152, s[2:3]
	v_alignbit_b32 v157, v151, v156, 30
	v_sub_u32_e32 v162, 0, v161
	v_cndmask_b32_e64 v152, v155, v152, s[20:21]
	v_xor_b32_e32 v157, v157, v162
	v_alignbit_b32 v154, v153, v152, v159
	v_cndmask_b32_e64 v153, v154, v153, s[6:7]
	v_ffbh_u32_e32 v155, v157
	v_alignbit_b32 v154, v156, v153, 30
	v_min_u32_e32 v155, 32, v155
	v_alignbit_b32 v152, v153, v152, 30
	v_xor_b32_e32 v154, v154, v162
	v_sub_u32_e32 v156, 31, v155
	v_xor_b32_e32 v152, v152, v162
	v_alignbit_b32 v157, v157, v154, v156
	v_alignbit_b32 v152, v154, v152, v156
	v_alignbit_b32 v153, v157, v152, 9
	v_ffbh_u32_e32 v154, v153
	v_min_u32_e32 v154, 32, v154
	v_lshrrev_b32_e32 v160, 29, v151
	v_not_b32_e32 v156, v154
	v_alignbit_b32 v152, v153, v152, v156
	v_lshlrev_b32_e32 v153, 31, v160
	v_or_b32_e32 v156, 0x33000000, v153
	v_add_lshl_u32 v154, v154, v155, 23
	v_lshrrev_b32_e32 v152, 9, v152
	v_sub_u32_e32 v154, v156, v154
	v_or_b32_e32 v153, 0.5, v153
	v_lshlrev_b32_e32 v155, 23, v155
	v_or_b32_e32 v152, v154, v152
	v_lshrrev_b32_e32 v154, 9, v157
	v_sub_u32_e32 v153, v153, v155
	v_or_b32_e32 v153, v154, v153
	v_mul_f32_e32 v154, 0x3fc90fda, v153
	v_fma_f32 v155, v153, s18, -v154
	v_fmamk_f32 v153, v153, 0x33a22168, v155
	v_fmac_f32_e32 v153, 0x3fc90fda, v152
	v_lshrrev_b32_e32 v151, 30, v151
	v_add_f32_e32 v65, v154, v153
	v_add_u32_e32 v67, v161, v151
.LBB0_902:
	s_andn2_saveexec_b64 s[2:3], s[12:13]
	s_cbranch_execz .LBB0_904
	s_mov_b32 s18, 0x3f22f983
	v_mul_f32_e64 v151, |v59|, s18
	v_rndne_f32_e32 v151, v151
	s_mov_b32 s18, 0xbfc90fda
	v_cvt_i32_f32_e32 v67, v151
	v_fma_f32 v152, v151, s18, |v59|
	v_fmamk_f32 v152, v151, 0xb3a22168, v152
	v_fmamk_f32 v65, v151, 0xa7c234c4, v152
.LBB0_904:
	s_or_b64 exec, exec, s[2:3]
	s_mov_b64 vcc, s[96:97]
	s_waitcnt vmcnt(62)
	v_mul_f32_e32 v2, 0x42000000, v45
	v_mul_f32_e32 v2, v53, v2
	s_mov_b32 s5, 0x3fb8aa3b
	v_mul_f32_e32 v3, 0x3fb8aa3b, v2
	v_fma_f32 v4, v2, s5, -v3
	v_rndne_f32_e32 v5, v3
	v_fmac_f32_e32 v4, 0x32a5705f, v2
	v_sub_f32_e32 v3, v3, v5
	v_add_f32_e32 v3, v3, v4
	v_exp_f32_e32 v3, v3
	v_cvt_i32_f32_e32 v4, v5
	s_lshl_b32 s14, s4, 7
	s_mov_b32 s4, 0xc2ce8ed0
	v_cmp_ngt_f32_e64 s[2:3], s4, v2
	v_ldexp_f32 v3, v3, v4
	s_mov_b32 s12, 0x42b17218
	v_cndmask_b32_e64 v3, 0, v3, s[2:3]
	v_mov_b32_e32 v85, 0x7f800000
	v_cmp_nlt_f32_e64 s[2:3], s12, v2
	v_mov_b32_e32 v79, 0x3c0881c4
	v_mov_b32_e32 v71, 0xbab64f3b
	v_cndmask_b32_e64 v2, v85, v3, s[2:3]
	v_mul_f32_e32 v3, v34, v34
	v_fmamk_f32 v4, v3, 0xb94c1982, v79
	v_fmaak_f32 v4, v3, v4, 0xbe2aaa9d
	v_mul_f32_e32 v4, v3, v4
	v_fmac_f32_e32 v34, v34, v4
	v_fmamk_f32 v4, v3, 0x37d75334, v71
	v_fmaak_f32 v4, v3, v4, 0x3d2aabf7
	v_fmaak_f32 v4, v3, v4, 0xbf000004
	v_fma_f32 v3, v3, v4, 1.0
	v_lshlrev_b32_e32 v4, 30, v35
	v_and_b32_e32 v35, 1, v35
	v_cmp_eq_u32_e64 s[2:3], 0, v35
	v_xor_b32_e32 v32, v32, v30
	v_and_b32_e32 v4, 0x80000000, v4
	v_cndmask_b32_e64 v35, v3, v34, s[2:3]
	v_xor_b32_e32 v34, 0x80000000, v34
	v_xor_b32_e32 v32, v32, v35
	v_cndmask_b32_e64 v3, v34, v3, s[2:3]
	s_movk_i32 s11, 0x1f8
	v_xor_b32_e32 v32, v32, v4
	v_xor_b32_e32 v3, v3, v4
	v_mov_b32_e32 v77, 0x7fc00000
	v_cmp_class_f32_e64 s[2:3], v30, s11
	v_mov_b32_e32 v5, 0
	v_mov_b32_e32 v89, 0xbe2aaa9d
	v_cndmask_b32_e64 v35, v77, v32, s[2:3]
	v_cndmask_b32_e64 v34, v77, v3, s[2:3]
	v_mov_b32_e32 v73, 0x3d2aabf7
	v_mov_b32_e32 v83, 0xbf000004
	s_brev_b32 s10, 1
	v_pk_mul_f32 v[2:3], v[2:3], v[34:35] op_sel_hi:[0,1]
	v_pk_mul_f32 v[106:107], v[2:3], 0 op_sel_hi:[1,0]
	v_cmp_lt_i32_e64 s[2:3], 0, v43
	v_pk_fma_f32 v[34:35], v[2:3], 0, v[106:107] op_sel:[0,0,1] op_sel_hi:[1,0,1] neg_lo:[0,0,1] neg_hi:[0,0,1]
	v_pk_fma_f32 v[56:57], v[2:3], 0, v[106:107] op_sel_hi:[1,0,0]
	s_nop 0
	v_mov_b32_e32 v35, v57
	v_pk_add_f32 v[104:105], v[34:35], v[8:9]
	s_nop 0
	v_pk_mul_f32 v[8:9], v[2:3], v[104:105]
	s_nop 0
	v_sub_f32_e32 v4, v8, v9
	v_pk_mul_f32 v[8:9], v[2:3], v[104:105] op_sel:[1,0] op_sel_hi:[0,1]
	v_add_f32_e32 v100, v4, v41
	v_add_f32_e32 v4, v8, v9
	v_add_f32_e32 v102, v4, v40
	s_waitcnt vmcnt(42)
	v_pk_mul_f32 v[8:9], v[2:3], v[102:103] op_sel:[1,0] op_sel_hi:[0,0]
	v_pk_fma_f32 v[34:35], v[2:3], v[100:101], v[8:9] neg_lo:[0,0,1] neg_hi:[0,0,1]
	v_pk_fma_f32 v[8:9], v[2:3], v[100:101], v[8:9] op_sel_hi:[1,0,1]
	s_nop 0
	v_mov_b32_e32 v35, v9
	v_pk_add_f32 v[98:99], v[34:35], v[6:7]
	s_nop 0
	v_pk_mul_f32 v[6:7], v[2:3], v[98:99]
	s_nop 0
	v_sub_f32_e32 v4, v6, v7
	v_pk_mul_f32 v[6:7], v[2:3], v[98:99] op_sel:[1,0] op_sel_hi:[0,1]
	v_add_f32_e32 v94, v4, v38
	v_add_f32_e32 v4, v6, v7
	v_add_f32_e32 v96, v4, v36
	v_pk_mul_f32 v[6:7], v[2:3], v[96:97] op_sel:[1,0] op_sel_hi:[0,0]
	v_pk_fma_f32 v[8:9], v[2:3], v[94:95], v[6:7] neg_lo:[0,0,1] neg_hi:[0,0,1]
	v_pk_fma_f32 v[6:7], v[2:3], v[94:95], v[6:7] op_sel_hi:[1,0,1]
	s_nop 0
	v_mov_b32_e32 v9, v7
	v_pk_add_f32 v[92:93], v[8:9], v[12:13]
	s_nop 0
	v_pk_mul_f32 v[6:7], v[2:3], v[92:93]
	s_nop 0
	v_sub_f32_e32 v4, v6, v7
	v_pk_mul_f32 v[6:7], v[2:3], v[92:93] op_sel:[1,0] op_sel_hi:[0,1]
	v_add_f32_e32 v88, v4, v49
	v_add_f32_e32 v4, v6, v7
	v_add_f32_e32 v90, v4, v48
	s_waitcnt vmcnt(39)
; __device__ __forceinline__ void ssm_scan(LAS float* L, int item, const float* lam_re, const float* lam_im, const float* log_dt, const float* S, f16* X) {
;     ...
;     for (int i = 0; i < 33; ++i) { const float s_r = vr[i], s_i = vi[i]; vr[i] = hr; vi[i] = hi; const float nr = tr * hr - ti * hi + s_r, ni = tr * hi + ti * hr + s_i; hr = nr; hi = ni; }
	v_pk_mul_f32 v[6:7], v[2:3], v[90:91] op_sel:[1,0] op_sel_hi:[0,0]
	v_pk_fma_f32 v[8:9], v[2:3], v[88:89], v[6:7] neg_lo:[0,0,1] neg_hi:[0,0,1]
	v_pk_fma_f32 v[6:7], v[2:3], v[88:89], v[6:7] op_sel_hi:[1,0,1]
	s_nop 0
	v_mov_b32_e32 v9, v7
	v_pk_add_f32 v[86:87], v[8:9], v[10:11]
	s_nop 0
	v_pk_mul_f32 v[6:7], v[2:3], v[86:87]
	s_nop 0
	v_sub_f32_e32 v4, v6, v7
	v_pk_mul_f32 v[6:7], v[2:3], v[86:87] op_sel:[1,0] op_sel_hi:[0,1]
	v_add_f32_e32 v82, v4, v44
	v_add_f32_e32 v4, v6, v7
	v_add_f32_e32 v84, v4, v42
	v_pk_mul_f32 v[6:7], v[2:3], v[84:85] op_sel:[1,0] op_sel_hi:[0,0]
	v_pk_fma_f32 v[8:9], v[2:3], v[82:83], v[6:7] neg_lo:[0,0,1] neg_hi:[0,0,1]
	v_pk_fma_f32 v[6:7], v[2:3], v[82:83], v[6:7] op_sel_hi:[1,0,1]
	s_nop 0
	v_mov_b32_e32 v9, v7
	v_pk_add_f32 v[80:81], v[8:9], v[16:17]
	s_nop 0
	v_pk_mul_f32 v[6:7], v[2:3], v[80:81]
	s_nop 0
	v_sub_f32_e32 v4, v6, v7
	v_pk_mul_f32 v[6:7], v[2:3], v[80:81] op_sel:[1,0] op_sel_hi:[0,1]
	v_add_f32_e32 v76, v4, v95
	v_add_f32_e32 v4, v6, v7
	v_add_f32_e32 v78, v4, v97
	v_pk_mul_f32 v[6:7], v[2:3], v[78:79] op_sel:[1,0] op_sel_hi:[0,0]
	v_pk_fma_f32 v[8:9], v[2:3], v[76:77], v[6:7] neg_lo:[0,0,1] neg_hi:[0,0,1]
	v_pk_fma_f32 v[6:7], v[2:3], v[76:77], v[6:7] op_sel_hi:[1,0,1]
	s_nop 0
	v_mov_b32_e32 v9, v7
	v_pk_add_f32 v[74:75], v[8:9], v[14:15]
	s_nop 0
	v_pk_mul_f32 v[6:7], v[2:3], v[74:75]
	s_nop 0
	v_sub_f32_e32 v4, v6, v7
	v_pk_mul_f32 v[6:7], v[2:3], v[74:75] op_sel:[1,0] op_sel_hi:[0,1]
	v_add_f32_e32 v70, v4, v101
	v_add_f32_e32 v4, v6, v7
	v_add_f32_e32 v72, v4, v103
	v_pk_mul_f32 v[6:7], v[2:3], v[72:73] op_sel:[1,0] op_sel_hi:[0,0]
	v_pk_fma_f32 v[8:9], v[2:3], v[70:71], v[6:7] neg_lo:[0,0,1] neg_hi:[0,0,1]
	v_pk_fma_f32 v[6:7], v[2:3], v[70:71], v[6:7] op_sel_hi:[1,0,1]
	s_nop 0
	v_mov_b32_e32 v9, v7
	v_pk_add_f32 v[68:69], v[8:9], v[20:21]
	s_nop 0
	v_pk_mul_f32 v[6:7], v[2:3], v[68:69]
	s_nop 0
	v_sub_f32_e32 v4, v6, v7
	v_pk_mul_f32 v[6:7], v[2:3], v[68:69] op_sel:[1,0] op_sel_hi:[0,1]
	v_add_f32_e32 v64, v4, v91
	v_add_f32_e32 v4, v6, v7
	s_waitcnt vmcnt(38)
	v_add_f32_e32 v66, v4, v114
	v_pk_mul_f32 v[6:7], v[2:3], v[66:67] op_sel:[1,0] op_sel_hi:[0,0]
	v_pk_fma_f32 v[8:9], v[2:3], v[64:65], v[6:7] neg_lo:[0,0,1] neg_hi:[0,0,1]
	v_pk_fma_f32 v[6:7], v[2:3], v[64:65], v[6:7] op_sel_hi:[1,0,1]
	s_nop 0
	v_mov_b32_e32 v9, v7
	s_waitcnt vmcnt(36)
	v_pk_add_f32 v[62:63], v[8:9], v[18:19]
	s_nop 0
	v_pk_mul_f32 v[6:7], v[2:3], v[62:63]
	s_nop 0
	v_sub_f32_e32 v4, v6, v7
	v_pk_mul_f32 v[6:7], v[2:3], v[62:63] op_sel:[1,0] op_sel_hi:[0,1]
	s_waitcnt vmcnt(35)
	v_add_f32_e32 v58, v4, v115
	v_add_f32_e32 v4, v6, v7
	s_waitcnt vmcnt(34)
	v_add_f32_e32 v60, v4, v116
	v_pk_mul_f32 v[6:7], v[2:3], v[60:61] op_sel:[1,0] op_sel_hi:[0,0]
	v_pk_fma_f32 v[8:9], v[2:3], v[58:59], v[6:7] neg_lo:[0,0,1] neg_hi:[0,0,1]
	v_pk_fma_f32 v[6:7], v[2:3], v[58:59], v[6:7] op_sel_hi:[1,0,1]
	s_nop 0
	v_mov_b32_e32 v9, v7
	s_waitcnt vmcnt(32)
	v_pk_add_f32 v[56:57], v[8:9], v[24:25]
	s_nop 0
	v_pk_mul_f32 v[6:7], v[2:3], v[56:57]
	s_nop 0
	v_sub_f32_e32 v4, v6, v7
	v_pk_mul_f32 v[6:7], v[2:3], v[56:57] op_sel:[1,0] op_sel_hi:[0,1]
	s_waitcnt vmcnt(31)
	v_add_f32_e32 v52, v4, v117
	v_add_f32_e32 v4, v6, v7
	s_waitcnt vmcnt(30)
	v_add_f32_e32 v54, v4, v118
	v_pk_mul_f32 v[6:7], v[2:3], v[54:55] op_sel:[1,0] op_sel_hi:[0,0]
	v_pk_fma_f32 v[8:9], v[2:3], v[52:53], v[6:7] neg_lo:[0,0,1] neg_hi:[0,0,1]
	v_pk_fma_f32 v[6:7], v[2:3], v[52:53], v[6:7] op_sel_hi:[1,0,1]
	s_nop 0
	v_mov_b32_e32 v9, v7
	s_waitcnt vmcnt(28)
	v_pk_add_f32 v[48:49], v[8:9], v[22:23]
	s_nop 0
	v_pk_mul_f32 v[6:7], v[2:3], v[48:49]
	s_nop 0
	v_sub_f32_e32 v4, v6, v7
	v_pk_mul_f32 v[6:7], v[2:3], v[48:49] op_sel:[1,0] op_sel_hi:[0,1]
	s_waitcnt vmcnt(27)
	v_add_f32_e32 v42, v4, v119
	v_add_f32_e32 v4, v6, v7
	s_waitcnt vmcnt(26)
	v_add_f32_e32 v44, v4, v120
	v_pk_mul_f32 v[6:7], v[2:3], v[44:45] op_sel:[1,0] op_sel_hi:[0,0]
	v_pk_fma_f32 v[8:9], v[2:3], v[42:43], v[6:7] neg_lo:[0,0,1] neg_hi:[0,0,1]
	v_pk_fma_f32 v[6:7], v[2:3], v[42:43], v[6:7] op_sel_hi:[1,0,1]
	s_nop 0
	v_mov_b32_e32 v9, v7
	s_waitcnt vmcnt(24)
	v_pk_add_f32 v[40:41], v[8:9], v[28:29]
	s_nop 0
	v_pk_mul_f32 v[6:7], v[2:3], v[40:41]
	s_nop 0
	v_sub_f32_e32 v4, v6, v7
	v_pk_mul_f32 v[6:7], v[2:3], v[40:41] op_sel:[1,0] op_sel_hi:[0,1]
	s_waitcnt vmcnt(23)
	v_add_f32_e32 v36, v4, v121
	v_add_f32_e32 v4, v6, v7
	s_waitcnt vmcnt(22)
	v_add_f32_e32 v38, v4, v122
	v_pk_mul_f32 v[6:7], v[2:3], v[38:39] op_sel:[1,0] op_sel_hi:[0,0]
	v_pk_fma_f32 v[8:9], v[2:3], v[36:37], v[6:7] neg_lo:[0,0,1] neg_hi:[0,0,1]
	v_pk_fma_f32 v[6:7], v[2:3], v[36:37], v[6:7] op_sel_hi:[1,0,1]
	s_nop 0
	v_mov_b32_e32 v9, v7
	s_waitcnt vmcnt(20)
; __device__ __forceinline__ void ssm_scan(LAS float* L, int item, const float* lam_re, const float* lam_im, const float* log_dt, const float* S, f16* X) {
;     ...
;     for (int i = 0; i < 33; ++i) { const float s_r = vr[i], s_i = vi[i]; vr[i] = hr; vi[i] = hi; const float nr = tr * hr - ti * hi + s_r, ni = tr * hi + ti * hr + s_i; hr = nr; hi = ni; }
;     L[(seg * 64 + n) * 2] = hr; L[(seg * 64 + n) * 2 + 1] = hi;
;     __syncthreads();
;     float ir = 0.f, ii = 0.f;
;     for (int k = 0; k < seg; ++k) { const float er = L[(k * 64 + n) * 2], ei = L[(k * 64 + n) * 2 + 1]; const float nr = sr * ir - si * ii + er, ni = sr * ii + si * ir + ei; ir = nr; ii = ni; }
	v_pk_add_f32 v[34:35], v[8:9], v[26:27]
	s_nop 0
	v_pk_mul_f32 v[6:7], v[2:3], v[34:35]
	s_nop 0
	v_sub_f32_e32 v4, v6, v7
	v_pk_mul_f32 v[6:7], v[2:3], v[34:35] op_sel:[1,0] op_sel_hi:[0,1]
	s_waitcnt vmcnt(19)
	v_add_f32_e32 v30, v4, v123
	v_add_f32_e32 v4, v6, v7
	s_waitcnt vmcnt(18)
	v_add_f32_e32 v32, v4, v124
	v_pk_mul_f32 v[6:7], v[2:3], v[32:33] op_sel:[1,0] op_sel_hi:[0,0]
	v_pk_fma_f32 v[8:9], v[2:3], v[30:31], v[6:7] neg_lo:[0,0,1] neg_hi:[0,0,1]
	v_pk_fma_f32 v[6:7], v[2:3], v[30:31], v[6:7] op_sel_hi:[1,0,1]
	s_nop 0
	v_mov_b32_e32 v9, v7
	s_waitcnt vmcnt(16)
	v_pk_add_f32 v[28:29], v[8:9], v[50:51]
	s_nop 0
	v_pk_mul_f32 v[6:7], v[2:3], v[28:29]
	s_nop 0
	v_sub_f32_e32 v4, v6, v7
	v_pk_mul_f32 v[6:7], v[2:3], v[28:29] op_sel:[1,0] op_sel_hi:[0,1]
	s_waitcnt vmcnt(15)
	v_add_f32_e32 v24, v4, v125
	v_add_f32_e32 v4, v6, v7
	s_waitcnt vmcnt(14)
	v_add_f32_e32 v26, v4, v126
	v_pk_mul_f32 v[6:7], v[2:3], v[26:27] op_sel:[1,0] op_sel_hi:[0,0]
	v_pk_fma_f32 v[8:9], v[2:3], v[24:25], v[6:7] neg_lo:[0,0,1] neg_hi:[0,0,1]
	v_pk_fma_f32 v[6:7], v[2:3], v[24:25], v[6:7] op_sel_hi:[1,0,1]
	s_nop 0
	v_mov_b32_e32 v9, v7
	s_waitcnt vmcnt(12)
	v_pk_add_f32 v[22:23], v[8:9], v[46:47]
	s_nop 0
	v_pk_mul_f32 v[6:7], v[2:3], v[22:23]
	s_nop 0
	v_sub_f32_e32 v4, v6, v7
	v_pk_mul_f32 v[6:7], v[2:3], v[22:23] op_sel:[1,0] op_sel_hi:[0,1]
	s_waitcnt vmcnt(11)
	v_add_f32_e32 v18, v4, v127
	v_add_f32_e32 v4, v6, v7
	s_waitcnt vmcnt(10)
	v_add_f32_e32 v20, v4, v128
	v_pk_mul_f32 v[6:7], v[2:3], v[20:21] op_sel:[1,0] op_sel_hi:[0,0]
	v_pk_fma_f32 v[8:9], v[2:3], v[18:19], v[6:7] neg_lo:[0,0,1] neg_hi:[0,0,1]
	v_pk_fma_f32 v[6:7], v[2:3], v[18:19], v[6:7] op_sel_hi:[1,0,1]
	s_nop 0
	v_mov_b32_e32 v9, v7
	s_waitcnt vmcnt(8)
	v_pk_add_f32 v[16:17], v[8:9], v[112:113]
	s_nop 0
	v_pk_mul_f32 v[6:7], v[2:3], v[16:17]
	s_nop 0
	v_sub_f32_e32 v4, v6, v7
	v_pk_mul_f32 v[6:7], v[2:3], v[16:17] op_sel:[1,0] op_sel_hi:[0,1]
	s_waitcnt vmcnt(7)
	v_add_f32_e32 v12, v4, v129
	v_add_f32_e32 v4, v6, v7
	s_waitcnt vmcnt(6)
	v_add_f32_e32 v14, v4, v131
	v_pk_mul_f32 v[6:7], v[2:3], v[14:15] op_sel:[1,0] op_sel_hi:[0,0]
	v_pk_fma_f32 v[8:9], v[2:3], v[12:13], v[6:7] neg_lo:[0,0,1] neg_hi:[0,0,1]
	v_pk_fma_f32 v[6:7], v[2:3], v[12:13], v[6:7] op_sel_hi:[1,0,1]
	s_nop 0
	v_mov_b32_e32 v9, v7
	s_waitcnt vmcnt(4)
	v_pk_add_f32 v[10:11], v[8:9], v[110:111]
	s_nop 0
	v_pk_mul_f32 v[6:7], v[2:3], v[10:11]
	v_pk_mul_f32 v[8:9], v[2:3], v[10:11] op_sel:[1,0] op_sel_hi:[0,1]
	v_sub_f32_e32 v4, v6, v7
	s_waitcnt vmcnt(3)
	v_add_f32_e32 v6, v4, v134
	v_add_f32_e32 v4, v8, v9
	s_waitcnt vmcnt(2)
	v_add_f32_e32 v8, v4, v135
	v_pk_mul_f32 v[46:47], v[2:3], v[8:9] op_sel:[1,0] op_sel_hi:[0,0]
	v_pk_fma_f32 v[50:51], v[2:3], v[6:7], v[46:47] neg_lo:[0,0,1] neg_hi:[0,0,1]
	v_pk_fma_f32 v[46:47], v[2:3], v[6:7], v[46:47] op_sel_hi:[1,0,1]
	v_lshl_add_u32 v4, v37, 3, 0
	v_mov_b32_e32 v51, v47
	s_waitcnt vmcnt(0)
	v_pk_add_f32 v[46:47], v[50:51], v[108:109]
	ds_write_b64 v4, v[46:47]
	v_mov_b32_e32 v4, v5
	s_waitcnt lgkmcnt(0)
	s_barrier
	s_and_saveexec_b64 s[6:7], s[2:3]
	s_cbranch_execz .LBB0_918
	v_mul_f32_e32 v4, 0x44840000, v45
	v_mul_f32_e32 v4, v53, v4
	v_mul_f32_e32 v5, 0x3fb8aa3b, v4
	v_fma_f32 v7, v4, s5, -v5
	v_rndne_f32_e32 v9, v5
	v_fmac_f32_e32 v7, 0x32a5705f, v4
	v_sub_f32_e32 v5, v5, v9
	v_add_f32_e32 v5, v5, v7
	v_cvt_i32_f32_e32 v7, v9
	v_exp_f32_e32 v5, v5
	v_cmp_ngt_f32_e64 s[4:5], s4, v4
	v_and_b32_e32 v15, 1, v67
	v_lshlrev_b32_e32 v9, 30, v67
	v_ldexp_f32 v5, v5, v7
	v_cndmask_b32_e64 v5, 0, v5, s[4:5]
	v_cmp_nlt_f32_e64 s[4:5], s12, v4
	v_xor_b32_e32 v19, v61, v59
	v_and_b32_e32 v13, 0x80000000, v9
	v_cndmask_b32_e64 v4, v85, v5, s[4:5]
	v_mul_f32_e32 v5, v65, v65
	v_fmac_f32_e32 v79, 0xb94c1982, v5
	v_fmac_f32_e32 v71, 0x37d75334, v5
	v_fmac_f32_e32 v89, v5, v79
	v_fmac_f32_e32 v73, v5, v71
	v_mul_f32_e32 v7, v5, v89
	v_fmac_f32_e32 v83, v5, v73
	v_fmac_f32_e32 v65, v65, v7
	v_fma_f32 v5, v5, v83, 1.0
	v_cmp_eq_u32_e64 s[4:5], 0, v15
	s_mov_b32 s15, 0
	v_mov_b32_e32 v7, 0
	v_cndmask_b32_e64 v15, v5, v65, s[4:5]
	v_xor_b32_e32 v15, v19, v15
	v_xor_b32_e32 v13, v15, v13
	v_xor_b32_e32 v15, 0x80000000, v65
	v_cndmask_b32_e64 v5, v15, v5, s[4:5]
	v_bitop3_b32 v5, v5, v9, s10 bitop3:0x78
	v_cmp_class_f32_e64 s[4:5], v59, s11
	v_lshlrev_b32_e32 v9, 3, v33
	s_nop 0
	v_cndmask_b32_e64 v5, v77, v5, s[4:5]
	v_mul_f32_e32 v46, v4, v5
	v_cndmask_b32_e64 v5, v77, v13, s[4:5]
	v_mul_f32_e32 v50, v4, v5
	v_mov_b32_e32 v4, 0
	v_mov_b32_e32 v47, v46
	v_cmp_lt_u32_e64 s[4:5], 7, v43
	v_mov_b32_e32 v5, v4
	s_and_saveexec_b64 s[10:11], s[4:5]
	s_cbranch_execz .LBB0_913
	v_add_u32_e32 v13, 0, v9
	v_and_b32_e32 v7, 0x7ffffff8, v43
	v_mov_b32_e32 v51, v50
	s_mov_b64 s[12:13], 0
	v_mov_b32_e32 v5, v4
